# M-phase: DMA issue spread between MFMAs; sigmoid gate 1/(1+e) via single v_rcp_f32 (f32, 1 ulp) instead of the IEEE div ladder
# speedup vs baseline: 1.0384x; 1.0171x over previous
; DI int get_tid() { int t = threadIdx.x; asm volatile("" : "+v"(t)); return t; }
; DI f32x16 mfma(bf16x8 a, bf16x8 b, f32x16 c) { return __builtin_amdgcn_mfma_f32_32x32x16_bf16(a, b, c, 0, 0, 0); }
;     ...
;   const int tid = get_tid(), lane = tid & 63, wave = tid >> 6, l32 = lane & 31, hh = lane >> 5;
;   const int wf = wave >> 2, wt = wave & 3;
;   const int crow = tid >> 3, q = tid & 7;
;   const int gc = q ^ ((crow >> 1) & 7);
;   const u16* wp = W + (size_t)crow * ldw + gc * 8;
;   const u16* xp = X + (size_t)crow * ldx + gc * 8;
;   char* lw = lds + tid * 16;
;   const int xr = (l32 >> 1) & 7;
;   const int abase = (wf * NFB * 32 + l32) * DROW;
;   const int bbase = 256 * DROW + (wt * NTB * 32 + l32) * DROW;
;     ...
;   __syncthreads();
;   DMA_ISSUE(0, 0)
;   asm volatile("s_waitcnt vmcnt(0)" ::: "memory");
;   __builtin_amdgcn_s_barrier();
;   for (int kt = 0; kt < nk; ++kt) {
;     const char* cur = lds + (kt & 1) * DBUF;
;     if (kt + 1 < nk) DMA_ISSUE((kt + 1) & 1, kt + 1)
; #pragma unroll(NTB == 1 ? 2 : 4)
;     for (int s = 0; s < 4; ++s) {
;       const int ro = ((2 * s + hh) ^ xr) * 16;
;       bf16x8 bfr[NTB];
; #pragma unroll
;       for (int tb = 0; tb < NTB; ++tb) bfr[tb] = *(const bf16x8*)(cur + bbase + tb * 32 * DROW + ro);
; #pragma unroll
;       for (int fb = 0; fb < NFB; ++fb) {
;         const bf16x8 afr = *(const bf16x8*)(cur + abase + fb * 32 * DROW + ro);
; #pragma unroll
;         for (int tb = 0; tb < NTB; ++tb) acc[tb * NFB + fb] = mfma(afr, bfr[tb], acc[tb * NFB + fb]);
;       }
;     }
; __global__ void __launch_bounds__(512) mega(Params p) {
;     ...
;         for (int n = 0; n < 3; ++n) {
;           f32x16 acc[4]; zero4(acc);
;           const size_t ooff = (n == 0) ? R_OA : (n == 1 ? R_OB : R_OC);
;           gemm_main<4, 1>((const u16*)(ws + OFF_WBR) + ((size_t)n * 1024 + ft * 256) * 512, 512, (const u16*)(ws + ooff) + (size_t)tt * 128 * 512, 512, 8, acc, lds);
.LBB0_25:
	s_cmp_eq_u32 s8, 1
	s_mov_b32 s0, 0x19db1000
	s_cselect_b32 s33, s0, 0x1bdb1000
	s_cmp_eq_u32 s8, 0
	s_cselect_b64 s[0:1], -1, 0
	s_and_b64 s[34:35], s[0:1], exec
	s_cselect_b32 s33, 0x6db1000, s33
	s_lshl_b32 s34, s8, 10
	s_add_u32 s34, s34, s54
	s_addc_u32 s35, 0, s55
	s_lshl_b64 s[66:67], s[34:35], 10
	v_mov_b32_e32 v8, v145
	s_add_u32 s66, s36, s66
	s_addc_u32 s67, s37, s67
	v_ashrrev_i32_e32 v2, 3, v8
	v_lshrrev_b32_e32 v0, 4, v8
	v_xor_b32_e32 v0, v0, v8
	v_ashrrev_i32_e32 v3, 31, v2
	s_add_u32 s68, s9, s33
	v_lshlrev_b64 v[4:5], 10, v[2:3]
	v_lshlrev_b32_e32 v0, 4, v0
	v_lshl_add_u32 v15, v8, 4, 0
	s_addc_u32 s69, s59, 0
	v_lshl_add_u64 v[2:3], s[66:67], 0, v[4:5]
	v_and_b32_e32 v0, 0x70, v0
	v_readfirstlane_b32 s33, v15
	v_add_u32_e32 v16, 0x2000, v15
	v_lshl_add_u64 v[2:3], v[2:3], 0, v[0:1]
	v_lshl_add_u64 v[4:5], s[68:69], 0, v[4:5]
	s_waitcnt vmcnt(0) lgkmcnt(0)
	s_barrier
	v_lshl_add_u64 v[4:5], v[4:5], 0, v[0:1]
	s_mov_b64 s[68:69], 0x10000
	v_lshl_add_u64 v[6:7], v[2:3], 0, s[68:69]
	v_lshl_add_u64 v[12:13], v[4:5], 0, s[68:69]
	v_lshl_add_u64 v[8:9], v[6:7], 0, s[68:69]
	v_lshl_add_u64 v[10:11], v[8:9], 0, s[68:69]
	s_add_u32 m0, s33, 0x0
	s_nop 0
	global_load_lds_dwordx4 v[2:3], off
	s_add_u32 m0, s33, 0x2000
	s_nop 0
	global_load_lds_dwordx4 v[6:7], off
	s_add_u32 m0, s33, 0x4000
	s_nop 0
	global_load_lds_dwordx4 v[8:9], off
	s_add_u32 m0, s33, 0x6000
	s_nop 0
	global_load_lds_dwordx4 v[10:11], off
	s_add_u32 m0, s33, 0x8000
	s_nop 0
	global_load_lds_dwordx4 v[4:5], off
	s_add_u32 m0, s33, 0xa000
	s_nop 0
	global_load_lds_dwordx4 v[12:13], off
	s_add_u32 m0, s33, 0xc000
	v_lshl_add_u64 v[2:3], v[2:3], 0, s[84:85]
	global_load_lds_dwordx4 v[2:3], off
	s_add_u32 m0, s33, 0xe000
	v_lshl_add_u64 v[6:7], v[6:7], 0, s[84:85]
	global_load_lds_dwordx4 v[6:7], off
	s_add_u32 m0, s33, 0x10000
	v_lshl_add_u64 v[8:9], v[8:9], 0, s[84:85]
	global_load_lds_dwordx4 v[8:9], off
	s_add_u32 m0, s33, 0x12000
	v_lshl_add_u64 v[10:11], v[10:11], 0, s[84:85]
	global_load_lds_dwordx4 v[10:11], off
	s_add_u32 m0, s33, 0x14000
	v_lshl_add_u64 v[4:5], v[4:5], 0, s[84:85]
	global_load_lds_dwordx4 v[4:5], off
	s_add_u32 m0, s33, 0x16000
	v_lshl_add_u64 v[12:13], v[12:13], 0, s[84:85]
	global_load_lds_dwordx4 v[12:13], off
	v_and_b32_e32 v238, 31, v145
	v_lshrrev_b32_e32 v239, 8, v145
	v_bfe_u32 v240, v145, 6, 2
	v_lshl_add_u32 v239, v239, 7, v238
	v_lshl_add_u32 v240, v240, 5, v238
	v_lshlrev_b32_e32 v239, 7, v239
	v_lshlrev_b32_e32 v240, 7, v240
	v_bfe_u32 v241, v145, 5, 1
	v_bfe_u32 v242, v145, 1, 3
	v_or_b32_e32 v243, 0, v241
	v_xor_b32_e32 v243, v243, v242
	v_lshlrev_b32_e32 v243, 4, v243
	v_add_u32_e32 v14, v239, v243
	v_add_u32_e32 v186, v240, v243
	v_or_b32_e32 v243, 2, v241
	v_xor_b32_e32 v243, v243, v242
	v_lshlrev_b32_e32 v243, 4, v243
	v_add_u32_e32 v15, v239, v243
	v_add_u32_e32 v189, v240, v243
	v_or_b32_e32 v243, 4, v241
	v_xor_b32_e32 v243, v243, v242
	v_lshlrev_b32_e32 v243, 4, v243
	v_add_u32_e32 v0, v239, v243
	v_add_u32_e32 v233, v240, v243
	v_or_b32_e32 v243, 6, v241
	v_xor_b32_e32 v243, v243, v242
	v_lshlrev_b32_e32 v243, 4, v243
	v_add_u32_e32 v184, v239, v243
	v_add_u32_e32 v234, v240, v243
	s_waitcnt vmcnt(6)
	s_barrier
	ds_read_b128 v[180:183], v186 offset:32768
	ds_read_b128 v[238:241], v14
	ds_read_b128 v[242:245], v14 offset:4096
	ds_read_b128 v[246:249], v14 offset:8192
	ds_read_b128 v[250:253], v14 offset:12288
	ds_read_b128 v[190:193], v189 offset:32768
	s_waitcnt lgkmcnt(4)
	v_mfma_f32_32x32x16_bf16 v[112:127], v[238:241], v[180:183], 0
	ds_read_b128 v[238:241], v15
	s_add_u32 m0, s33, 0x18000
	v_lshl_add_u64 v[2:3], v[2:3], 0, s[84:85]
	global_load_lds_dwordx4 v[2:3], off
	s_waitcnt lgkmcnt(4)
	v_mfma_f32_32x32x16_bf16 v[96:111], v[242:245], v[180:183], 0
	ds_read_b128 v[242:245], v15 offset:4096
	s_waitcnt lgkmcnt(4)
	v_mfma_f32_32x32x16_bf16 v[80:95], v[246:249], v[180:183], 0
	ds_read_b128 v[246:249], v15 offset:8192
	s_add_u32 m0, s33, 0x1a000
	v_lshl_add_u64 v[6:7], v[6:7], 0, s[84:85]
	global_load_lds_dwordx4 v[6:7], off
	s_waitcnt lgkmcnt(4)
	v_mfma_f32_32x32x16_bf16 v[64:79], v[250:253], v[180:183], 0
	ds_read_b128 v[250:253], v15 offset:12288
	ds_read_b128 v[180:183], v233 offset:32768
	s_waitcnt lgkmcnt(4)
	v_mfma_f32_32x32x16_bf16 v[112:127], v[238:241], v[190:193], v[112:127]
	ds_read_b128 v[238:241], v0
	s_add_u32 m0, s33, 0x1c000
	v_lshl_add_u64 v[8:9], v[8:9], 0, s[84:85]
	global_load_lds_dwordx4 v[8:9], off
	s_waitcnt lgkmcnt(4)
	v_mfma_f32_32x32x16_bf16 v[96:111], v[242:245], v[190:193], v[96:111]
	ds_read_b128 v[242:245], v0 offset:4096
	s_waitcnt lgkmcnt(4)
	v_mfma_f32_32x32x16_bf16 v[80:95], v[246:249], v[190:193], v[80:95]
	ds_read_b128 v[246:249], v0 offset:8192
	s_add_u32 m0, s33, 0x1e000
	v_lshl_add_u64 v[10:11], v[10:11], 0, s[84:85]
	global_load_lds_dwordx4 v[10:11], off
	s_waitcnt lgkmcnt(4)
	v_mfma_f32_32x32x16_bf16 v[64:79], v[250:253], v[190:193], v[64:79]
	ds_read_b128 v[250:253], v0 offset:12288
	ds_read_b128 v[190:193], v234 offset:32768
	s_waitcnt lgkmcnt(4)
	v_mfma_f32_32x32x16_bf16 v[112:127], v[238:241], v[180:183], v[112:127]
	ds_read_b128 v[238:241], v184
	s_add_u32 m0, s33, 0x20000
	v_lshl_add_u64 v[4:5], v[4:5], 0, s[84:85]
	global_load_lds_dwordx4 v[4:5], off
	s_waitcnt lgkmcnt(4)
	v_mfma_f32_32x32x16_bf16 v[96:111], v[242:245], v[180:183], v[96:111]
	ds_read_b128 v[242:245], v184 offset:4096
	s_waitcnt lgkmcnt(4)
	v_mfma_f32_32x32x16_bf16 v[80:95], v[246:249], v[180:183], v[80:95]
	ds_read_b128 v[246:249], v184 offset:8192
	s_add_u32 m0, s33, 0x22000
	v_lshl_add_u64 v[12:13], v[12:13], 0, s[84:85]
	global_load_lds_dwordx4 v[12:13], off
	s_waitcnt lgkmcnt(4)
	v_mfma_f32_32x32x16_bf16 v[64:79], v[250:253], v[180:183], v[64:79]
	ds_read_b128 v[250:253], v184 offset:12288
	s_waitcnt lgkmcnt(3)
	v_mfma_f32_32x32x16_bf16 v[112:127], v[238:241], v[190:193], v[112:127]
	s_waitcnt lgkmcnt(2)
	v_mfma_f32_32x32x16_bf16 v[96:111], v[242:245], v[190:193], v[96:111]
	s_waitcnt lgkmcnt(1)
	v_mfma_f32_32x32x16_bf16 v[80:95], v[246:249], v[190:193], v[80:95]
	s_waitcnt lgkmcnt(0)
	v_mfma_f32_32x32x16_bf16 v[64:79], v[250:253], v[190:193], v[64:79]
	s_waitcnt vmcnt(6)
	s_barrier
; DI f32x16 mfma(bf16x8 a, bf16x8 b, f32x16 c) { return __builtin_amdgcn_mfma_f32_32x32x16_bf16(a, b, c, 0, 0, 0); }
;     ...
;   for (int kt = 0; kt < nk; ++kt) {
;     const char* cur = lds + (kt & 1) * DBUF;
;     if (kt + 1 < nk) DMA_ISSUE((kt + 1) & 1, kt + 1)
; #pragma unroll(NTB == 1 ? 2 : 4)
;     for (int s = 0; s < 4; ++s) {
;       const int ro = ((2 * s + hh) ^ xr) * 16;
;       bf16x8 bfr[NTB];
; #pragma unroll
;       for (int tb = 0; tb < NTB; ++tb) bfr[tb] = *(const bf16x8*)(cur + bbase + tb * 32 * DROW + ro);
; #pragma unroll
;       for (int fb = 0; fb < NFB; ++fb) {
;         const bf16x8 afr = *(const bf16x8*)(cur + abase + fb * 32 * DROW + ro);
; #pragma unroll
;         for (int tb = 0; tb < NTB; ++tb) acc[tb * NFB + fb] = mfma(afr, bfr[tb], acc[tb * NFB + fb]);
;       }
;     }
;     asm volatile("s_waitcnt vmcnt(0) lgkmcnt(0)" ::: "memory");
;     __builtin_amdgcn_s_barrier();
	v_add_u32_e32 v195, 0xc000, v186
	ds_read_b128 v[180:183], v195 offset:32768
	v_add_u32_e32 v194, 0xc000, v14
	ds_read_b128 v[238:241], v194
	ds_read_b128 v[242:245], v194 offset:4096
	ds_read_b128 v[246:249], v194 offset:8192
	ds_read_b128 v[250:253], v194 offset:12288
	v_add_u32_e32 v195, 0xc000, v189
	ds_read_b128 v[190:193], v195 offset:32768
	v_add_u32_e32 v194, 0xc000, v15
	s_waitcnt lgkmcnt(4)
	v_mfma_f32_32x32x16_bf16 v[112:127], v[238:241], v[180:183], v[112:127]
	ds_read_b128 v[238:241], v194
	s_add_u32 m0, s33, 0x0
	v_lshl_add_u64 v[2:3], v[2:3], 0, s[84:85]
	global_load_lds_dwordx4 v[2:3], off
	s_waitcnt lgkmcnt(4)
	v_mfma_f32_32x32x16_bf16 v[96:111], v[242:245], v[180:183], v[96:111]
	ds_read_b128 v[242:245], v194 offset:4096
	s_waitcnt lgkmcnt(4)
	v_mfma_f32_32x32x16_bf16 v[80:95], v[246:249], v[180:183], v[80:95]
	ds_read_b128 v[246:249], v194 offset:8192
	s_add_u32 m0, s33, 0x2000
	v_lshl_add_u64 v[6:7], v[6:7], 0, s[84:85]
	global_load_lds_dwordx4 v[6:7], off
	s_waitcnt lgkmcnt(4)
	v_mfma_f32_32x32x16_bf16 v[64:79], v[250:253], v[180:183], v[64:79]
	ds_read_b128 v[250:253], v194 offset:12288
	v_add_u32_e32 v195, 0xc000, v233
	ds_read_b128 v[180:183], v195 offset:32768
	v_add_u32_e32 v194, 0xc000, v0
	s_waitcnt lgkmcnt(4)
	v_mfma_f32_32x32x16_bf16 v[112:127], v[238:241], v[190:193], v[112:127]
	ds_read_b128 v[238:241], v194
	s_add_u32 m0, s33, 0x4000
	v_lshl_add_u64 v[8:9], v[8:9], 0, s[84:85]
	global_load_lds_dwordx4 v[8:9], off
	s_waitcnt lgkmcnt(4)
	v_mfma_f32_32x32x16_bf16 v[96:111], v[242:245], v[190:193], v[96:111]
	ds_read_b128 v[242:245], v194 offset:4096
	s_waitcnt lgkmcnt(4)
	v_mfma_f32_32x32x16_bf16 v[80:95], v[246:249], v[190:193], v[80:95]
	ds_read_b128 v[246:249], v194 offset:8192
	s_add_u32 m0, s33, 0x6000
	v_lshl_add_u64 v[10:11], v[10:11], 0, s[84:85]
	global_load_lds_dwordx4 v[10:11], off
	s_waitcnt lgkmcnt(4)
	v_mfma_f32_32x32x16_bf16 v[64:79], v[250:253], v[190:193], v[64:79]
	ds_read_b128 v[250:253], v194 offset:12288
	v_add_u32_e32 v195, 0xc000, v234
	ds_read_b128 v[190:193], v195 offset:32768
	v_add_u32_e32 v194, 0xc000, v184
	s_waitcnt lgkmcnt(4)
	v_mfma_f32_32x32x16_bf16 v[112:127], v[238:241], v[180:183], v[112:127]
	ds_read_b128 v[238:241], v194
	s_add_u32 m0, s33, 0x8000
	v_lshl_add_u64 v[4:5], v[4:5], 0, s[84:85]
	global_load_lds_dwordx4 v[4:5], off
	s_waitcnt lgkmcnt(4)
	v_mfma_f32_32x32x16_bf16 v[96:111], v[242:245], v[180:183], v[96:111]
	ds_read_b128 v[242:245], v194 offset:4096
	s_waitcnt lgkmcnt(4)
	v_mfma_f32_32x32x16_bf16 v[80:95], v[246:249], v[180:183], v[80:95]
	ds_read_b128 v[246:249], v194 offset:8192
	s_add_u32 m0, s33, 0xa000
	v_lshl_add_u64 v[12:13], v[12:13], 0, s[84:85]
	global_load_lds_dwordx4 v[12:13], off
	s_waitcnt lgkmcnt(4)
	v_mfma_f32_32x32x16_bf16 v[64:79], v[250:253], v[180:183], v[64:79]
	ds_read_b128 v[250:253], v194 offset:12288
	s_waitcnt lgkmcnt(3)
	v_mfma_f32_32x32x16_bf16 v[112:127], v[238:241], v[190:193], v[112:127]
	s_waitcnt lgkmcnt(2)
	v_mfma_f32_32x32x16_bf16 v[96:111], v[242:245], v[190:193], v[96:111]
	s_waitcnt lgkmcnt(1)
	v_mfma_f32_32x32x16_bf16 v[80:95], v[246:249], v[190:193], v[80:95]
	s_waitcnt lgkmcnt(0)
	v_mfma_f32_32x32x16_bf16 v[64:79], v[250:253], v[190:193], v[64:79]
	s_waitcnt vmcnt(6)
	s_barrier
	v_add_u32_e32 v195, 0x18000, v186
	ds_read_b128 v[180:183], v195 offset:32768
	v_add_u32_e32 v194, 0x18000, v14
	ds_read_b128 v[238:241], v194
	ds_read_b128 v[242:245], v194 offset:4096
	ds_read_b128 v[246:249], v194 offset:8192
	ds_read_b128 v[250:253], v194 offset:12288
	v_add_u32_e32 v195, 0x18000, v189
	ds_read_b128 v[190:193], v195 offset:32768
	v_add_u32_e32 v194, 0x18000, v15
	s_waitcnt lgkmcnt(4)
	v_mfma_f32_32x32x16_bf16 v[112:127], v[238:241], v[180:183], v[112:127]
	ds_read_b128 v[238:241], v194
	s_add_u32 m0, s33, 0xc000
	v_lshl_add_u64 v[2:3], v[2:3], 0, s[84:85]
	global_load_lds_dwordx4 v[2:3], off
	s_waitcnt lgkmcnt(4)
	v_mfma_f32_32x32x16_bf16 v[96:111], v[242:245], v[180:183], v[96:111]
	ds_read_b128 v[242:245], v194 offset:4096
	s_waitcnt lgkmcnt(4)
	v_mfma_f32_32x32x16_bf16 v[80:95], v[246:249], v[180:183], v[80:95]
	ds_read_b128 v[246:249], v194 offset:8192
	s_add_u32 m0, s33, 0xe000
	v_lshl_add_u64 v[6:7], v[6:7], 0, s[84:85]
	global_load_lds_dwordx4 v[6:7], off
	s_waitcnt lgkmcnt(4)
	v_mfma_f32_32x32x16_bf16 v[64:79], v[250:253], v[180:183], v[64:79]
	ds_read_b128 v[250:253], v194 offset:12288
	v_add_u32_e32 v195, 0x18000, v233
	ds_read_b128 v[180:183], v195 offset:32768
	v_add_u32_e32 v194, 0x18000, v0
	s_waitcnt lgkmcnt(4)
	v_mfma_f32_32x32x16_bf16 v[112:127], v[238:241], v[190:193], v[112:127]
	ds_read_b128 v[238:241], v194
	s_add_u32 m0, s33, 0x10000
	v_lshl_add_u64 v[8:9], v[8:9], 0, s[84:85]
	global_load_lds_dwordx4 v[8:9], off
	s_waitcnt lgkmcnt(4)
	v_mfma_f32_32x32x16_bf16 v[96:111], v[242:245], v[190:193], v[96:111]
	ds_read_b128 v[242:245], v194 offset:4096
	s_waitcnt lgkmcnt(4)
	v_mfma_f32_32x32x16_bf16 v[80:95], v[246:249], v[190:193], v[80:95]
	ds_read_b128 v[246:249], v194 offset:8192
	s_add_u32 m0, s33, 0x12000
	v_lshl_add_u64 v[10:11], v[10:11], 0, s[84:85]
	global_load_lds_dwordx4 v[10:11], off
	s_waitcnt lgkmcnt(4)
	v_mfma_f32_32x32x16_bf16 v[64:79], v[250:253], v[190:193], v[64:79]
	ds_read_b128 v[250:253], v194 offset:12288
	v_add_u32_e32 v195, 0x18000, v234
	ds_read_b128 v[190:193], v195 offset:32768
	v_add_u32_e32 v194, 0x18000, v184
	s_waitcnt lgkmcnt(4)
	v_mfma_f32_32x32x16_bf16 v[112:127], v[238:241], v[180:183], v[112:127]
	ds_read_b128 v[238:241], v194
	s_add_u32 m0, s33, 0x14000
	v_lshl_add_u64 v[4:5], v[4:5], 0, s[84:85]
	global_load_lds_dwordx4 v[4:5], off
	s_waitcnt lgkmcnt(4)
	v_mfma_f32_32x32x16_bf16 v[96:111], v[242:245], v[180:183], v[96:111]
	ds_read_b128 v[242:245], v194 offset:4096
	s_waitcnt lgkmcnt(4)
	v_mfma_f32_32x32x16_bf16 v[80:95], v[246:249], v[180:183], v[80:95]
	ds_read_b128 v[246:249], v194 offset:8192
	s_add_u32 m0, s33, 0x16000
	v_lshl_add_u64 v[12:13], v[12:13], 0, s[84:85]
	global_load_lds_dwordx4 v[12:13], off
	s_waitcnt lgkmcnt(4)
	v_mfma_f32_32x32x16_bf16 v[64:79], v[250:253], v[180:183], v[64:79]
	ds_read_b128 v[250:253], v194 offset:12288
	s_waitcnt lgkmcnt(3)
	v_mfma_f32_32x32x16_bf16 v[112:127], v[238:241], v[190:193], v[112:127]
	s_waitcnt lgkmcnt(2)
	v_mfma_f32_32x32x16_bf16 v[96:111], v[242:245], v[190:193], v[96:111]
	s_waitcnt lgkmcnt(1)
	v_mfma_f32_32x32x16_bf16 v[80:95], v[246:249], v[190:193], v[80:95]
	s_waitcnt lgkmcnt(0)
	v_mfma_f32_32x32x16_bf16 v[64:79], v[250:253], v[190:193], v[64:79]
	s_waitcnt vmcnt(6)
	s_barrier
; DI f32x16 mfma(bf16x8 a, bf16x8 b, f32x16 c) { return __builtin_amdgcn_mfma_f32_32x32x16_bf16(a, b, c, 0, 0, 0); }
;     ...
;   for (int kt = 0; kt < nk; ++kt) {
;     const char* cur = lds + (kt & 1) * DBUF;
;     if (kt + 1 < nk) DMA_ISSUE((kt + 1) & 1, kt + 1)
; #pragma unroll(NTB == 1 ? 2 : 4)
;     for (int s = 0; s < 4; ++s) {
;       const int ro = ((2 * s + hh) ^ xr) * 16;
;       bf16x8 bfr[NTB];
; #pragma unroll
;       for (int tb = 0; tb < NTB; ++tb) bfr[tb] = *(const bf16x8*)(cur + bbase + tb * 32 * DROW + ro);
; #pragma unroll
;       for (int fb = 0; fb < NFB; ++fb) {
;         const bf16x8 afr = *(const bf16x8*)(cur + abase + fb * 32 * DROW + ro);
; #pragma unroll
;         for (int tb = 0; tb < NTB; ++tb) acc[tb * NFB + fb] = mfma(afr, bfr[tb], acc[tb * NFB + fb]);
;       }
;     }
;     asm volatile("s_waitcnt vmcnt(0) lgkmcnt(0)" ::: "memory");
;     __builtin_amdgcn_s_barrier();
	ds_read_b128 v[180:183], v186 offset:32768
	ds_read_b128 v[238:241], v14
	ds_read_b128 v[242:245], v14 offset:4096
	ds_read_b128 v[246:249], v14 offset:8192
	ds_read_b128 v[250:253], v14 offset:12288
	ds_read_b128 v[190:193], v189 offset:32768
	s_waitcnt lgkmcnt(4)
	v_mfma_f32_32x32x16_bf16 v[112:127], v[238:241], v[180:183], v[112:127]
	ds_read_b128 v[238:241], v15
	s_add_u32 m0, s33, 0x18000
	v_lshl_add_u64 v[2:3], v[2:3], 0, s[84:85]
	global_load_lds_dwordx4 v[2:3], off
	s_waitcnt lgkmcnt(4)
	v_mfma_f32_32x32x16_bf16 v[96:111], v[242:245], v[180:183], v[96:111]
	ds_read_b128 v[242:245], v15 offset:4096
	s_waitcnt lgkmcnt(4)
	v_mfma_f32_32x32x16_bf16 v[80:95], v[246:249], v[180:183], v[80:95]
	ds_read_b128 v[246:249], v15 offset:8192
	s_add_u32 m0, s33, 0x1a000
	v_lshl_add_u64 v[6:7], v[6:7], 0, s[84:85]
	global_load_lds_dwordx4 v[6:7], off
	s_waitcnt lgkmcnt(4)
	v_mfma_f32_32x32x16_bf16 v[64:79], v[250:253], v[180:183], v[64:79]
	ds_read_b128 v[250:253], v15 offset:12288
	ds_read_b128 v[180:183], v233 offset:32768
	s_waitcnt lgkmcnt(4)
	v_mfma_f32_32x32x16_bf16 v[112:127], v[238:241], v[190:193], v[112:127]
	ds_read_b128 v[238:241], v0
	s_add_u32 m0, s33, 0x1c000
	v_lshl_add_u64 v[8:9], v[8:9], 0, s[84:85]
	global_load_lds_dwordx4 v[8:9], off
	s_waitcnt lgkmcnt(4)
	v_mfma_f32_32x32x16_bf16 v[96:111], v[242:245], v[190:193], v[96:111]
	ds_read_b128 v[242:245], v0 offset:4096
	s_waitcnt lgkmcnt(4)
	v_mfma_f32_32x32x16_bf16 v[80:95], v[246:249], v[190:193], v[80:95]
	ds_read_b128 v[246:249], v0 offset:8192
	s_add_u32 m0, s33, 0x1e000
	v_lshl_add_u64 v[10:11], v[10:11], 0, s[84:85]
	global_load_lds_dwordx4 v[10:11], off
	s_waitcnt lgkmcnt(4)
	v_mfma_f32_32x32x16_bf16 v[64:79], v[250:253], v[190:193], v[64:79]
	ds_read_b128 v[250:253], v0 offset:12288
	ds_read_b128 v[190:193], v234 offset:32768
	s_waitcnt lgkmcnt(4)
	v_mfma_f32_32x32x16_bf16 v[112:127], v[238:241], v[180:183], v[112:127]
	ds_read_b128 v[238:241], v184
	s_add_u32 m0, s33, 0x20000
	v_lshl_add_u64 v[4:5], v[4:5], 0, s[84:85]
	global_load_lds_dwordx4 v[4:5], off
	s_waitcnt lgkmcnt(4)
	v_mfma_f32_32x32x16_bf16 v[96:111], v[242:245], v[180:183], v[96:111]
	ds_read_b128 v[242:245], v184 offset:4096
	s_waitcnt lgkmcnt(4)
	v_mfma_f32_32x32x16_bf16 v[80:95], v[246:249], v[180:183], v[80:95]
	ds_read_b128 v[246:249], v184 offset:8192
	s_add_u32 m0, s33, 0x22000
	v_lshl_add_u64 v[12:13], v[12:13], 0, s[84:85]
	global_load_lds_dwordx4 v[12:13], off
	s_waitcnt lgkmcnt(4)
	v_mfma_f32_32x32x16_bf16 v[64:79], v[250:253], v[180:183], v[64:79]
	ds_read_b128 v[250:253], v184 offset:12288
	s_waitcnt lgkmcnt(3)
	v_mfma_f32_32x32x16_bf16 v[112:127], v[238:241], v[190:193], v[112:127]
	s_waitcnt lgkmcnt(2)
	v_mfma_f32_32x32x16_bf16 v[96:111], v[242:245], v[190:193], v[96:111]
	s_waitcnt lgkmcnt(1)
	v_mfma_f32_32x32x16_bf16 v[80:95], v[246:249], v[190:193], v[80:95]
	s_waitcnt lgkmcnt(0)
	v_mfma_f32_32x32x16_bf16 v[64:79], v[250:253], v[190:193], v[64:79]
	s_waitcnt vmcnt(6)
	s_barrier
	v_add_u32_e32 v195, 0xc000, v186
	ds_read_b128 v[180:183], v195 offset:32768
	v_add_u32_e32 v194, 0xc000, v14
	ds_read_b128 v[238:241], v194
	ds_read_b128 v[242:245], v194 offset:4096
	ds_read_b128 v[246:249], v194 offset:8192
	ds_read_b128 v[250:253], v194 offset:12288
	v_add_u32_e32 v195, 0xc000, v189
	ds_read_b128 v[190:193], v195 offset:32768
	v_add_u32_e32 v194, 0xc000, v15
	s_waitcnt lgkmcnt(4)
	v_mfma_f32_32x32x16_bf16 v[112:127], v[238:241], v[180:183], v[112:127]
	ds_read_b128 v[238:241], v194
	s_add_u32 m0, s33, 0x0
	v_lshl_add_u64 v[2:3], v[2:3], 0, s[84:85]
	global_load_lds_dwordx4 v[2:3], off
	s_waitcnt lgkmcnt(4)
	v_mfma_f32_32x32x16_bf16 v[96:111], v[242:245], v[180:183], v[96:111]
	ds_read_b128 v[242:245], v194 offset:4096
	s_waitcnt lgkmcnt(4)
	v_mfma_f32_32x32x16_bf16 v[80:95], v[246:249], v[180:183], v[80:95]
	ds_read_b128 v[246:249], v194 offset:8192
	s_add_u32 m0, s33, 0x2000
	v_lshl_add_u64 v[6:7], v[6:7], 0, s[84:85]
	global_load_lds_dwordx4 v[6:7], off
	s_waitcnt lgkmcnt(4)
	v_mfma_f32_32x32x16_bf16 v[64:79], v[250:253], v[180:183], v[64:79]
	ds_read_b128 v[250:253], v194 offset:12288
	v_add_u32_e32 v195, 0xc000, v233
	ds_read_b128 v[180:183], v195 offset:32768
	v_add_u32_e32 v194, 0xc000, v0
	s_waitcnt lgkmcnt(4)
	v_mfma_f32_32x32x16_bf16 v[112:127], v[238:241], v[190:193], v[112:127]
	ds_read_b128 v[238:241], v194
	s_add_u32 m0, s33, 0x4000
	v_lshl_add_u64 v[8:9], v[8:9], 0, s[84:85]
	global_load_lds_dwordx4 v[8:9], off
	s_waitcnt lgkmcnt(4)
	v_mfma_f32_32x32x16_bf16 v[96:111], v[242:245], v[190:193], v[96:111]
	ds_read_b128 v[242:245], v194 offset:4096
	s_waitcnt lgkmcnt(4)
	v_mfma_f32_32x32x16_bf16 v[80:95], v[246:249], v[190:193], v[80:95]
	ds_read_b128 v[246:249], v194 offset:8192
	s_add_u32 m0, s33, 0x6000
	v_lshl_add_u64 v[10:11], v[10:11], 0, s[84:85]
	global_load_lds_dwordx4 v[10:11], off
	s_waitcnt lgkmcnt(4)
	v_mfma_f32_32x32x16_bf16 v[64:79], v[250:253], v[190:193], v[64:79]
	ds_read_b128 v[250:253], v194 offset:12288
	v_add_u32_e32 v195, 0xc000, v234
	ds_read_b128 v[190:193], v195 offset:32768
	v_add_u32_e32 v194, 0xc000, v184
	s_waitcnt lgkmcnt(4)
	v_mfma_f32_32x32x16_bf16 v[112:127], v[238:241], v[180:183], v[112:127]
	ds_read_b128 v[238:241], v194
	s_add_u32 m0, s33, 0x8000
	v_lshl_add_u64 v[4:5], v[4:5], 0, s[84:85]
	global_load_lds_dwordx4 v[4:5], off
	s_waitcnt lgkmcnt(4)
	v_mfma_f32_32x32x16_bf16 v[96:111], v[242:245], v[180:183], v[96:111]
	ds_read_b128 v[242:245], v194 offset:4096
	s_waitcnt lgkmcnt(4)
	v_mfma_f32_32x32x16_bf16 v[80:95], v[246:249], v[180:183], v[80:95]
	ds_read_b128 v[246:249], v194 offset:8192
	s_add_u32 m0, s33, 0xa000
	v_lshl_add_u64 v[12:13], v[12:13], 0, s[84:85]
	global_load_lds_dwordx4 v[12:13], off
	s_waitcnt lgkmcnt(4)
	v_mfma_f32_32x32x16_bf16 v[64:79], v[250:253], v[180:183], v[64:79]
	ds_read_b128 v[250:253], v194 offset:12288
	s_waitcnt lgkmcnt(3)
	v_mfma_f32_32x32x16_bf16 v[112:127], v[238:241], v[190:193], v[112:127]
	s_waitcnt lgkmcnt(2)
	v_mfma_f32_32x32x16_bf16 v[96:111], v[242:245], v[190:193], v[96:111]
	s_waitcnt lgkmcnt(1)
	v_mfma_f32_32x32x16_bf16 v[80:95], v[246:249], v[190:193], v[80:95]
	s_waitcnt lgkmcnt(0)
	v_mfma_f32_32x32x16_bf16 v[64:79], v[250:253], v[190:193], v[64:79]
	s_waitcnt vmcnt(6)
	s_barrier
; DI f32x16 mfma(bf16x8 a, bf16x8 b, f32x16 c) { return __builtin_amdgcn_mfma_f32_32x32x16_bf16(a, b, c, 0, 0, 0); }
;     ...
;   for (int kt = 0; kt < nk; ++kt) {
;     const char* cur = lds + (kt & 1) * DBUF;
;     if (kt + 1 < nk) DMA_ISSUE((kt + 1) & 1, kt + 1)
; #pragma unroll(NTB == 1 ? 2 : 4)
;     for (int s = 0; s < 4; ++s) {
;       const int ro = ((2 * s + hh) ^ xr) * 16;
;       bf16x8 bfr[NTB];
; #pragma unroll
;       for (int tb = 0; tb < NTB; ++tb) bfr[tb] = *(const bf16x8*)(cur + bbase + tb * 32 * DROW + ro);
; #pragma unroll
;       for (int fb = 0; fb < NFB; ++fb) {
;         const bf16x8 afr = *(const bf16x8*)(cur + abase + fb * 32 * DROW + ro);
; #pragma unroll
;         for (int tb = 0; tb < NTB; ++tb) acc[tb * NFB + fb] = mfma(afr, bfr[tb], acc[tb * NFB + fb]);
;       }
;     }
;     asm volatile("s_waitcnt vmcnt(0) lgkmcnt(0)" ::: "memory");
;     __builtin_amdgcn_s_barrier();
; __global__ void __launch_bounds__(512) mega(Params p) {
;     ...
;           gemm_main<4, 1>((const u16*)(ws + OFF_WG) + ((size_t)n * 1024 + ft * 256) * 1024, 1024, (const u16*)(ws + OFF_H) + (size_t)tt * 128 * 1024, 1024, 16, acc, lds);
	v_add_u32_e32 v195, 0x18000, v186
	ds_read_b128 v[180:183], v195 offset:32768
	v_add_u32_e32 v194, 0x18000, v14
	ds_read_b128 v[238:241], v194
	ds_read_b128 v[242:245], v194 offset:4096
	ds_read_b128 v[246:249], v194 offset:8192
	ds_read_b128 v[250:253], v194 offset:12288
	v_add_u32_e32 v195, 0x18000, v189
	ds_read_b128 v[190:193], v195 offset:32768
	v_add_u32_e32 v194, 0x18000, v15
	s_waitcnt lgkmcnt(4)
	v_mfma_f32_32x32x16_bf16 v[112:127], v[238:241], v[180:183], v[112:127]
	ds_read_b128 v[238:241], v194
	s_add_u32 m0, s33, 0xc000
	v_lshl_add_u64 v[2:3], v[2:3], 0, s[84:85]
	global_load_lds_dwordx4 v[2:3], off
	s_waitcnt lgkmcnt(4)
	v_mfma_f32_32x32x16_bf16 v[96:111], v[242:245], v[180:183], v[96:111]
	ds_read_b128 v[242:245], v194 offset:4096
	s_waitcnt lgkmcnt(4)
	v_mfma_f32_32x32x16_bf16 v[80:95], v[246:249], v[180:183], v[80:95]
	ds_read_b128 v[246:249], v194 offset:8192
	s_add_u32 m0, s33, 0xe000
	v_lshl_add_u64 v[6:7], v[6:7], 0, s[84:85]
	global_load_lds_dwordx4 v[6:7], off
	s_waitcnt lgkmcnt(4)
	v_mfma_f32_32x32x16_bf16 v[64:79], v[250:253], v[180:183], v[64:79]
	ds_read_b128 v[250:253], v194 offset:12288
	v_add_u32_e32 v195, 0x18000, v233
	ds_read_b128 v[180:183], v195 offset:32768
	v_add_u32_e32 v194, 0x18000, v0
	s_waitcnt lgkmcnt(4)
	v_mfma_f32_32x32x16_bf16 v[112:127], v[238:241], v[190:193], v[112:127]
	ds_read_b128 v[238:241], v194
	s_add_u32 m0, s33, 0x10000
	v_lshl_add_u64 v[8:9], v[8:9], 0, s[84:85]
	global_load_lds_dwordx4 v[8:9], off
	s_waitcnt lgkmcnt(4)
	v_mfma_f32_32x32x16_bf16 v[96:111], v[242:245], v[190:193], v[96:111]
	ds_read_b128 v[242:245], v194 offset:4096
	s_waitcnt lgkmcnt(4)
	v_mfma_f32_32x32x16_bf16 v[80:95], v[246:249], v[190:193], v[80:95]
	ds_read_b128 v[246:249], v194 offset:8192
	s_add_u32 m0, s33, 0x12000
	v_lshl_add_u64 v[10:11], v[10:11], 0, s[84:85]
	global_load_lds_dwordx4 v[10:11], off
	s_waitcnt lgkmcnt(4)
	v_mfma_f32_32x32x16_bf16 v[64:79], v[250:253], v[190:193], v[64:79]
	ds_read_b128 v[250:253], v194 offset:12288
	v_add_u32_e32 v195, 0x18000, v234
	ds_read_b128 v[190:193], v195 offset:32768
	v_add_u32_e32 v194, 0x18000, v184
	s_waitcnt lgkmcnt(4)
	v_mfma_f32_32x32x16_bf16 v[112:127], v[238:241], v[180:183], v[112:127]
	ds_read_b128 v[238:241], v194
	s_add_u32 m0, s33, 0x14000
	v_lshl_add_u64 v[4:5], v[4:5], 0, s[84:85]
	global_load_lds_dwordx4 v[4:5], off
	s_waitcnt lgkmcnt(4)
	v_mfma_f32_32x32x16_bf16 v[96:111], v[242:245], v[180:183], v[96:111]
	ds_read_b128 v[242:245], v194 offset:4096
	s_waitcnt lgkmcnt(4)
	v_mfma_f32_32x32x16_bf16 v[80:95], v[246:249], v[180:183], v[80:95]
	ds_read_b128 v[246:249], v194 offset:8192
	s_add_u32 m0, s33, 0x16000
	v_lshl_add_u64 v[12:13], v[12:13], 0, s[84:85]
	global_load_lds_dwordx4 v[12:13], off
	s_waitcnt lgkmcnt(4)
	v_mfma_f32_32x32x16_bf16 v[64:79], v[250:253], v[180:183], v[64:79]
	ds_read_b128 v[250:253], v194 offset:12288
	s_waitcnt lgkmcnt(3)
	v_mfma_f32_32x32x16_bf16 v[112:127], v[238:241], v[190:193], v[112:127]
	s_waitcnt lgkmcnt(2)
	v_mfma_f32_32x32x16_bf16 v[96:111], v[242:245], v[190:193], v[96:111]
	s_waitcnt lgkmcnt(1)
	v_mfma_f32_32x32x16_bf16 v[80:95], v[246:249], v[190:193], v[80:95]
	s_waitcnt lgkmcnt(0)
	v_mfma_f32_32x32x16_bf16 v[64:79], v[250:253], v[190:193], v[64:79]
	s_waitcnt vmcnt(6)
	s_barrier
	ds_read_b128 v[180:183], v186 offset:32768
	ds_read_b128 v[238:241], v14
	ds_read_b128 v[242:245], v14 offset:4096
	ds_read_b128 v[246:249], v14 offset:8192
	ds_read_b128 v[250:253], v14 offset:12288
	ds_read_b128 v[190:193], v189 offset:32768
	s_waitcnt lgkmcnt(4)
	v_mfma_f32_32x32x16_bf16 v[112:127], v[238:241], v[180:183], v[112:127]
	ds_read_b128 v[238:241], v15
	s_lshl_b64 s[34:35], s[34:35], 11
	s_add_u32 s34, s38, s34
	s_addc_u32 s35, s39, s35
	v_ashrrev_i32_e32 v18, 3, v145
	v_lshrrev_b32_e32 v16, 4, v145
	v_xor_b32_e32 v16, v16, v145
	v_ashrrev_i32_e32 v19, 31, v18
	v_lshlrev_b64 v[18:19], 11, v[18:19]
	v_lshlrev_b32_e32 v16, 4, v16
	v_and_b32_e32 v16, 0x70, v16
	v_mov_b32_e32 v17, 0
	v_lshl_add_u64 v[2:3], s[34:35], 0, v[18:19]
	v_lshl_add_u64 v[4:5], s[64:65], 0, v[18:19]
	v_lshl_add_u64 v[2:3], v[2:3], 0, v[16:17]
	v_lshl_add_u64 v[4:5], v[4:5], 0, v[16:17]
	s_mov_b64 s[68:69], 0x20000
	v_lshl_add_u64 v[6:7], v[2:3], 0, s[68:69]
	v_lshl_add_u64 v[12:13], v[4:5], 0, s[68:69]
	v_lshl_add_u64 v[8:9], v[6:7], 0, s[68:69]
	v_lshl_add_u64 v[10:11], v[8:9], 0, s[68:69]
	s_add_u32 m0, s33, 0x18000
	s_nop 0
	global_load_lds_dwordx4 v[2:3], off
	s_waitcnt lgkmcnt(4)
	v_mfma_f32_32x32x16_bf16 v[96:111], v[242:245], v[180:183], v[96:111]
	ds_read_b128 v[242:245], v15 offset:4096
	s_waitcnt lgkmcnt(4)
	v_mfma_f32_32x32x16_bf16 v[80:95], v[246:249], v[180:183], v[80:95]
	ds_read_b128 v[246:249], v15 offset:8192
	s_add_u32 m0, s33, 0x1a000
	s_nop 0
	global_load_lds_dwordx4 v[6:7], off
	s_waitcnt lgkmcnt(4)
	v_mfma_f32_32x32x16_bf16 v[64:79], v[250:253], v[180:183], v[64:79]
	ds_read_b128 v[250:253], v15 offset:12288
	ds_read_b128 v[180:183], v233 offset:32768
	s_waitcnt lgkmcnt(4)
	v_mfma_f32_32x32x16_bf16 v[112:127], v[238:241], v[190:193], v[112:127]
	ds_read_b128 v[238:241], v0
	s_add_u32 m0, s33, 0x1c000
	s_nop 0
	global_load_lds_dwordx4 v[8:9], off
	s_waitcnt lgkmcnt(4)
	v_mfma_f32_32x32x16_bf16 v[96:111], v[242:245], v[190:193], v[96:111]
	ds_read_b128 v[242:245], v0 offset:4096
	s_waitcnt lgkmcnt(4)
	v_mfma_f32_32x32x16_bf16 v[80:95], v[246:249], v[190:193], v[80:95]
	ds_read_b128 v[246:249], v0 offset:8192
	s_add_u32 m0, s33, 0x1e000
	s_nop 0
	global_load_lds_dwordx4 v[10:11], off
	s_waitcnt lgkmcnt(4)
	v_mfma_f32_32x32x16_bf16 v[64:79], v[250:253], v[190:193], v[64:79]
	ds_read_b128 v[250:253], v0 offset:12288
	ds_read_b128 v[190:193], v234 offset:32768
	s_waitcnt lgkmcnt(4)
	v_mfma_f32_32x32x16_bf16 v[112:127], v[238:241], v[180:183], v[112:127]
	ds_read_b128 v[238:241], v184
	s_add_u32 m0, s33, 0x20000
	s_nop 0
	global_load_lds_dwordx4 v[4:5], off
	s_waitcnt lgkmcnt(4)
	v_mfma_f32_32x32x16_bf16 v[96:111], v[242:245], v[180:183], v[96:111]
	ds_read_b128 v[242:245], v184 offset:4096
	s_waitcnt lgkmcnt(4)
	v_mfma_f32_32x32x16_bf16 v[80:95], v[246:249], v[180:183], v[80:95]
	ds_read_b128 v[246:249], v184 offset:8192
	s_add_u32 m0, s33, 0x22000
	s_nop 0
	global_load_lds_dwordx4 v[12:13], off
	s_waitcnt lgkmcnt(4)
	v_mfma_f32_32x32x16_bf16 v[64:79], v[250:253], v[180:183], v[64:79]
	ds_read_b128 v[250:253], v184 offset:12288
	s_waitcnt lgkmcnt(3)
	v_mfma_f32_32x32x16_bf16 v[112:127], v[238:241], v[190:193], v[112:127]
	s_waitcnt lgkmcnt(2)
	v_mfma_f32_32x32x16_bf16 v[96:111], v[242:245], v[190:193], v[96:111]
	s_waitcnt lgkmcnt(1)
	v_mfma_f32_32x32x16_bf16 v[80:95], v[246:249], v[190:193], v[80:95]
	s_waitcnt lgkmcnt(0)
	v_mfma_f32_32x32x16_bf16 v[64:79], v[250:253], v[190:193], v[64:79]
	s_waitcnt vmcnt(6)
	s_barrier
; DI f32x16 mfma(bf16x8 a, bf16x8 b, f32x16 c) { return __builtin_amdgcn_mfma_f32_32x32x16_bf16(a, b, c, 0, 0, 0); }
;     ...
;   for (int kt = 0; kt < nk; ++kt) {
;     const char* cur = lds + (kt & 1) * DBUF;
;     if (kt + 1 < nk) DMA_ISSUE((kt + 1) & 1, kt + 1)
; #pragma unroll(NTB == 1 ? 2 : 4)
;     for (int s = 0; s < 4; ++s) {
;       const int ro = ((2 * s + hh) ^ xr) * 16;
;       bf16x8 bfr[NTB];
; #pragma unroll
;       for (int tb = 0; tb < NTB; ++tb) bfr[tb] = *(const bf16x8*)(cur + bbase + tb * 32 * DROW + ro);
; #pragma unroll
;       for (int fb = 0; fb < NFB; ++fb) {
;         const bf16x8 afr = *(const bf16x8*)(cur + abase + fb * 32 * DROW + ro);
; #pragma unroll
;         for (int tb = 0; tb < NTB; ++tb) acc[tb * NFB + fb] = mfma(afr, bfr[tb], acc[tb * NFB + fb]);
;       }
;     }
;     asm volatile("s_waitcnt vmcnt(0) lgkmcnt(0)" ::: "memory");
;     __builtin_amdgcn_s_barrier();
; __global__ void __launch_bounds__(512) mega(Params p) {
;     ...
;           zero4(acc);
;           gemm_main<4, 1>((const u16*)(ws + OFF_WG) + ((size_t)n * 1024 + ft * 256) * 1024, 1024, (const u16*)(ws + OFF_H) + (size_t)tt * 128 * 1024, 1024, 16, acc, lds);
	v_add_u32_e32 v195, 0xc000, v186
	ds_read_b128 v[180:183], v195 offset:32768
	v_add_u32_e32 v194, 0xc000, v14
	ds_read_b128 v[238:241], v194
	ds_read_b128 v[242:245], v194 offset:4096
	ds_read_b128 v[246:249], v194 offset:8192
	ds_read_b128 v[250:253], v194 offset:12288
	v_add_u32_e32 v195, 0xc000, v189
	ds_read_b128 v[190:193], v195 offset:32768
	v_add_u32_e32 v194, 0xc000, v15
	s_waitcnt lgkmcnt(4)
	v_mfma_f32_32x32x16_bf16 v[112:127], v[238:241], v[180:183], v[112:127]
	ds_read_b128 v[238:241], v194
	s_add_u32 m0, s33, 0x0
	v_lshl_add_u64 v[2:3], v[2:3], 0, s[84:85]
	global_load_lds_dwordx4 v[2:3], off
	s_waitcnt lgkmcnt(4)
	v_mfma_f32_32x32x16_bf16 v[96:111], v[242:245], v[180:183], v[96:111]
	ds_read_b128 v[242:245], v194 offset:4096
	s_waitcnt lgkmcnt(4)
	v_mfma_f32_32x32x16_bf16 v[80:95], v[246:249], v[180:183], v[80:95]
	ds_read_b128 v[246:249], v194 offset:8192
	s_add_u32 m0, s33, 0x2000
	v_lshl_add_u64 v[6:7], v[6:7], 0, s[84:85]
	global_load_lds_dwordx4 v[6:7], off
	s_waitcnt lgkmcnt(4)
	v_mfma_f32_32x32x16_bf16 v[64:79], v[250:253], v[180:183], v[64:79]
	ds_read_b128 v[250:253], v194 offset:12288
	v_add_u32_e32 v195, 0xc000, v233
	ds_read_b128 v[180:183], v195 offset:32768
	v_add_u32_e32 v194, 0xc000, v0
	s_waitcnt lgkmcnt(4)
	v_mfma_f32_32x32x16_bf16 v[112:127], v[238:241], v[190:193], v[112:127]
	ds_read_b128 v[238:241], v194
	s_add_u32 m0, s33, 0x4000
	v_lshl_add_u64 v[8:9], v[8:9], 0, s[84:85]
	global_load_lds_dwordx4 v[8:9], off
	s_waitcnt lgkmcnt(4)
	v_mfma_f32_32x32x16_bf16 v[96:111], v[242:245], v[190:193], v[96:111]
	ds_read_b128 v[242:245], v194 offset:4096
	s_waitcnt lgkmcnt(4)
	v_mfma_f32_32x32x16_bf16 v[80:95], v[246:249], v[190:193], v[80:95]
	ds_read_b128 v[246:249], v194 offset:8192
	s_add_u32 m0, s33, 0x6000
	v_lshl_add_u64 v[10:11], v[10:11], 0, s[84:85]
	global_load_lds_dwordx4 v[10:11], off
	s_waitcnt lgkmcnt(4)
	v_mfma_f32_32x32x16_bf16 v[64:79], v[250:253], v[190:193], v[64:79]
	ds_read_b128 v[250:253], v194 offset:12288
	v_add_u32_e32 v195, 0xc000, v234
	ds_read_b128 v[190:193], v195 offset:32768
	v_add_u32_e32 v194, 0xc000, v184
	s_waitcnt lgkmcnt(4)
	v_mfma_f32_32x32x16_bf16 v[112:127], v[238:241], v[180:183], v[112:127]
	ds_read_b128 v[238:241], v194
	s_add_u32 m0, s33, 0x8000
	v_lshl_add_u64 v[4:5], v[4:5], 0, s[84:85]
	global_load_lds_dwordx4 v[4:5], off
	s_waitcnt lgkmcnt(4)
	v_mfma_f32_32x32x16_bf16 v[96:111], v[242:245], v[180:183], v[96:111]
	ds_read_b128 v[242:245], v194 offset:4096
	s_waitcnt lgkmcnt(4)
	v_mfma_f32_32x32x16_bf16 v[80:95], v[246:249], v[180:183], v[80:95]
	ds_read_b128 v[246:249], v194 offset:8192
	s_add_u32 m0, s33, 0xa000
	v_lshl_add_u64 v[12:13], v[12:13], 0, s[84:85]
	global_load_lds_dwordx4 v[12:13], off
	s_waitcnt lgkmcnt(4)
	v_mfma_f32_32x32x16_bf16 v[64:79], v[250:253], v[180:183], v[64:79]
	ds_read_b128 v[250:253], v194 offset:12288
	s_waitcnt lgkmcnt(3)
	v_mfma_f32_32x32x16_bf16 v[112:127], v[238:241], v[190:193], v[112:127]
	s_waitcnt lgkmcnt(2)
	v_mfma_f32_32x32x16_bf16 v[96:111], v[242:245], v[190:193], v[96:111]
	s_waitcnt lgkmcnt(1)
	v_mfma_f32_32x32x16_bf16 v[80:95], v[246:249], v[190:193], v[80:95]
	s_waitcnt lgkmcnt(0)
	v_mfma_f32_32x32x16_bf16 v[64:79], v[250:253], v[190:193], v[64:79]
	s_waitcnt vmcnt(6)
	s_barrier
	v_add_u32_e32 v195, 0x18000, v186
	ds_read_b128 v[180:183], v195 offset:32768
	v_add_u32_e32 v194, 0x18000, v14
	ds_read_b128 v[238:241], v194
	ds_read_b128 v[242:245], v194 offset:4096
	ds_read_b128 v[246:249], v194 offset:8192
	ds_read_b128 v[250:253], v194 offset:12288
	v_add_u32_e32 v195, 0x18000, v189
	ds_read_b128 v[190:193], v195 offset:32768
	v_add_u32_e32 v194, 0x18000, v15
	s_waitcnt lgkmcnt(4)
	v_mfma_f32_32x32x16_bf16 v[128:143], v[238:241], v[180:183], 0
	ds_read_b128 v[238:241], v194
	s_add_u32 m0, s33, 0xc000
	v_lshl_add_u64 v[2:3], v[2:3], 0, s[84:85]
	global_load_lds_dwordx4 v[2:3], off
	s_waitcnt lgkmcnt(4)
	v_mfma_f32_32x32x16_bf16 v[48:63], v[242:245], v[180:183], 0
	ds_read_b128 v[242:245], v194 offset:4096
	s_waitcnt lgkmcnt(4)
	v_mfma_f32_32x32x16_bf16 v[32:47], v[246:249], v[180:183], 0
	ds_read_b128 v[246:249], v194 offset:8192
	s_add_u32 m0, s33, 0xe000
	v_lshl_add_u64 v[6:7], v[6:7], 0, s[84:85]
	global_load_lds_dwordx4 v[6:7], off
	s_waitcnt lgkmcnt(4)
	v_mfma_f32_32x32x16_bf16 v[16:31], v[250:253], v[180:183], 0
	ds_read_b128 v[250:253], v194 offset:12288
	v_add_u32_e32 v195, 0x18000, v233
	ds_read_b128 v[180:183], v195 offset:32768
	v_add_u32_e32 v194, 0x18000, v0
	s_waitcnt lgkmcnt(4)
	v_mfma_f32_32x32x16_bf16 v[128:143], v[238:241], v[190:193], v[128:143]
	ds_read_b128 v[238:241], v194
	s_add_u32 m0, s33, 0x10000
	v_lshl_add_u64 v[8:9], v[8:9], 0, s[84:85]
	global_load_lds_dwordx4 v[8:9], off
	s_waitcnt lgkmcnt(4)
	v_mfma_f32_32x32x16_bf16 v[48:63], v[242:245], v[190:193], v[48:63]
	ds_read_b128 v[242:245], v194 offset:4096
	s_waitcnt lgkmcnt(4)
	v_mfma_f32_32x32x16_bf16 v[32:47], v[246:249], v[190:193], v[32:47]
	ds_read_b128 v[246:249], v194 offset:8192
	s_add_u32 m0, s33, 0x12000
	v_lshl_add_u64 v[10:11], v[10:11], 0, s[84:85]
	global_load_lds_dwordx4 v[10:11], off
	s_waitcnt lgkmcnt(4)
	v_mfma_f32_32x32x16_bf16 v[16:31], v[250:253], v[190:193], v[16:31]
	ds_read_b128 v[250:253], v194 offset:12288
	v_add_u32_e32 v195, 0x18000, v234
	ds_read_b128 v[190:193], v195 offset:32768
	v_add_u32_e32 v194, 0x18000, v184
	s_waitcnt lgkmcnt(4)
	v_mfma_f32_32x32x16_bf16 v[128:143], v[238:241], v[180:183], v[128:143]
	ds_read_b128 v[238:241], v194
	s_add_u32 m0, s33, 0x14000
	v_lshl_add_u64 v[4:5], v[4:5], 0, s[84:85]
	global_load_lds_dwordx4 v[4:5], off
	s_waitcnt lgkmcnt(4)
	v_mfma_f32_32x32x16_bf16 v[48:63], v[242:245], v[180:183], v[48:63]
	ds_read_b128 v[242:245], v194 offset:4096
	s_waitcnt lgkmcnt(4)
	v_mfma_f32_32x32x16_bf16 v[32:47], v[246:249], v[180:183], v[32:47]
	ds_read_b128 v[246:249], v194 offset:8192
	s_add_u32 m0, s33, 0x16000
	v_lshl_add_u64 v[12:13], v[12:13], 0, s[84:85]
	global_load_lds_dwordx4 v[12:13], off
	s_waitcnt lgkmcnt(4)
	v_mfma_f32_32x32x16_bf16 v[16:31], v[250:253], v[180:183], v[16:31]
	ds_read_b128 v[250:253], v194 offset:12288
	s_waitcnt lgkmcnt(3)
	v_mfma_f32_32x32x16_bf16 v[128:143], v[238:241], v[190:193], v[128:143]
	s_waitcnt lgkmcnt(2)
	v_mfma_f32_32x32x16_bf16 v[48:63], v[242:245], v[190:193], v[48:63]
	s_waitcnt lgkmcnt(1)
	v_mfma_f32_32x32x16_bf16 v[32:47], v[246:249], v[190:193], v[32:47]
	s_waitcnt lgkmcnt(0)
	v_mfma_f32_32x32x16_bf16 v[16:31], v[250:253], v[190:193], v[16:31]
	s_waitcnt vmcnt(6)
	s_barrier
; DI f32x16 mfma(bf16x8 a, bf16x8 b, f32x16 c) { return __builtin_amdgcn_mfma_f32_32x32x16_bf16(a, b, c, 0, 0, 0); }
;     ...
;   for (int kt = 0; kt < nk; ++kt) {
;     const char* cur = lds + (kt & 1) * DBUF;
;     if (kt + 1 < nk) DMA_ISSUE((kt + 1) & 1, kt + 1)
; #pragma unroll(NTB == 1 ? 2 : 4)
;     for (int s = 0; s < 4; ++s) {
;       const int ro = ((2 * s + hh) ^ xr) * 16;
;       bf16x8 bfr[NTB];
; #pragma unroll
;       for (int tb = 0; tb < NTB; ++tb) bfr[tb] = *(const bf16x8*)(cur + bbase + tb * 32 * DROW + ro);
; #pragma unroll
;       for (int fb = 0; fb < NFB; ++fb) {
;         const bf16x8 afr = *(const bf16x8*)(cur + abase + fb * 32 * DROW + ro);
; #pragma unroll
;         for (int tb = 0; tb < NTB; ++tb) acc[tb * NFB + fb] = mfma(afr, bfr[tb], acc[tb * NFB + fb]);
;       }
;     }
;     asm volatile("s_waitcnt vmcnt(0) lgkmcnt(0)" ::: "memory");
;     __builtin_amdgcn_s_barrier();
	ds_read_b128 v[180:183], v186 offset:32768
	ds_read_b128 v[238:241], v14
	ds_read_b128 v[242:245], v14 offset:4096
	ds_read_b128 v[246:249], v14 offset:8192
	ds_read_b128 v[250:253], v14 offset:12288
	ds_read_b128 v[190:193], v189 offset:32768
	s_waitcnt lgkmcnt(4)
	v_mfma_f32_32x32x16_bf16 v[128:143], v[238:241], v[180:183], v[128:143]
	ds_read_b128 v[238:241], v15
	s_add_u32 m0, s33, 0x18000
	v_lshl_add_u64 v[2:3], v[2:3], 0, s[84:85]
	global_load_lds_dwordx4 v[2:3], off
	s_waitcnt lgkmcnt(4)
	v_mfma_f32_32x32x16_bf16 v[48:63], v[242:245], v[180:183], v[48:63]
	ds_read_b128 v[242:245], v15 offset:4096
	s_waitcnt lgkmcnt(4)
	v_mfma_f32_32x32x16_bf16 v[32:47], v[246:249], v[180:183], v[32:47]
	ds_read_b128 v[246:249], v15 offset:8192
	s_add_u32 m0, s33, 0x1a000
	v_lshl_add_u64 v[6:7], v[6:7], 0, s[84:85]
	global_load_lds_dwordx4 v[6:7], off
	s_waitcnt lgkmcnt(4)
	v_mfma_f32_32x32x16_bf16 v[16:31], v[250:253], v[180:183], v[16:31]
	ds_read_b128 v[250:253], v15 offset:12288
	ds_read_b128 v[180:183], v233 offset:32768
	s_waitcnt lgkmcnt(4)
	v_mfma_f32_32x32x16_bf16 v[128:143], v[238:241], v[190:193], v[128:143]
	ds_read_b128 v[238:241], v0
	s_add_u32 m0, s33, 0x1c000
	v_lshl_add_u64 v[8:9], v[8:9], 0, s[84:85]
	global_load_lds_dwordx4 v[8:9], off
	s_waitcnt lgkmcnt(4)
	v_mfma_f32_32x32x16_bf16 v[48:63], v[242:245], v[190:193], v[48:63]
	ds_read_b128 v[242:245], v0 offset:4096
	s_waitcnt lgkmcnt(4)
	v_mfma_f32_32x32x16_bf16 v[32:47], v[246:249], v[190:193], v[32:47]
	ds_read_b128 v[246:249], v0 offset:8192
	s_add_u32 m0, s33, 0x1e000
	v_lshl_add_u64 v[10:11], v[10:11], 0, s[84:85]
	global_load_lds_dwordx4 v[10:11], off
	s_waitcnt lgkmcnt(4)
	v_mfma_f32_32x32x16_bf16 v[16:31], v[250:253], v[190:193], v[16:31]
	ds_read_b128 v[250:253], v0 offset:12288
	ds_read_b128 v[190:193], v234 offset:32768
	s_waitcnt lgkmcnt(4)
	v_mfma_f32_32x32x16_bf16 v[128:143], v[238:241], v[180:183], v[128:143]
	ds_read_b128 v[238:241], v184
	s_add_u32 m0, s33, 0x20000
	v_lshl_add_u64 v[4:5], v[4:5], 0, s[84:85]
	global_load_lds_dwordx4 v[4:5], off
	s_waitcnt lgkmcnt(4)
	v_mfma_f32_32x32x16_bf16 v[48:63], v[242:245], v[180:183], v[48:63]
	ds_read_b128 v[242:245], v184 offset:4096
	s_waitcnt lgkmcnt(4)
	v_mfma_f32_32x32x16_bf16 v[32:47], v[246:249], v[180:183], v[32:47]
	ds_read_b128 v[246:249], v184 offset:8192
	s_add_u32 m0, s33, 0x22000
	v_lshl_add_u64 v[12:13], v[12:13], 0, s[84:85]
	global_load_lds_dwordx4 v[12:13], off
	s_waitcnt lgkmcnt(4)
	v_mfma_f32_32x32x16_bf16 v[16:31], v[250:253], v[180:183], v[16:31]
	ds_read_b128 v[250:253], v184 offset:12288
	s_waitcnt lgkmcnt(3)
	v_mfma_f32_32x32x16_bf16 v[128:143], v[238:241], v[190:193], v[128:143]
	s_waitcnt lgkmcnt(2)
	v_mfma_f32_32x32x16_bf16 v[48:63], v[242:245], v[190:193], v[48:63]
	s_waitcnt lgkmcnt(1)
	v_mfma_f32_32x32x16_bf16 v[32:47], v[246:249], v[190:193], v[32:47]
	s_waitcnt lgkmcnt(0)
	v_mfma_f32_32x32x16_bf16 v[16:31], v[250:253], v[190:193], v[16:31]
	s_waitcnt vmcnt(6)
	s_barrier
	v_add_u32_e32 v195, 0xc000, v186
	ds_read_b128 v[180:183], v195 offset:32768
	v_add_u32_e32 v194, 0xc000, v14
	ds_read_b128 v[238:241], v194
	ds_read_b128 v[242:245], v194 offset:4096
	ds_read_b128 v[246:249], v194 offset:8192
	ds_read_b128 v[250:253], v194 offset:12288
	v_add_u32_e32 v195, 0xc000, v189
	ds_read_b128 v[190:193], v195 offset:32768
	v_add_u32_e32 v194, 0xc000, v15
	s_waitcnt lgkmcnt(4)
	v_mfma_f32_32x32x16_bf16 v[128:143], v[238:241], v[180:183], v[128:143]
	ds_read_b128 v[238:241], v194
	s_add_u32 m0, s33, 0x0
	v_lshl_add_u64 v[2:3], v[2:3], 0, s[84:85]
	global_load_lds_dwordx4 v[2:3], off
	s_waitcnt lgkmcnt(4)
	v_mfma_f32_32x32x16_bf16 v[48:63], v[242:245], v[180:183], v[48:63]
	ds_read_b128 v[242:245], v194 offset:4096
	s_waitcnt lgkmcnt(4)
	v_mfma_f32_32x32x16_bf16 v[32:47], v[246:249], v[180:183], v[32:47]
	ds_read_b128 v[246:249], v194 offset:8192
	s_add_u32 m0, s33, 0x2000
	v_lshl_add_u64 v[6:7], v[6:7], 0, s[84:85]
	global_load_lds_dwordx4 v[6:7], off
	s_waitcnt lgkmcnt(4)
	v_mfma_f32_32x32x16_bf16 v[16:31], v[250:253], v[180:183], v[16:31]
	ds_read_b128 v[250:253], v194 offset:12288
	v_add_u32_e32 v195, 0xc000, v233
	ds_read_b128 v[180:183], v195 offset:32768
	v_add_u32_e32 v194, 0xc000, v0
	s_waitcnt lgkmcnt(4)
	v_mfma_f32_32x32x16_bf16 v[128:143], v[238:241], v[190:193], v[128:143]
	ds_read_b128 v[238:241], v194
	s_add_u32 m0, s33, 0x4000
	v_lshl_add_u64 v[8:9], v[8:9], 0, s[84:85]
	global_load_lds_dwordx4 v[8:9], off
	s_waitcnt lgkmcnt(4)
	v_mfma_f32_32x32x16_bf16 v[48:63], v[242:245], v[190:193], v[48:63]
	ds_read_b128 v[242:245], v194 offset:4096
	s_waitcnt lgkmcnt(4)
	v_mfma_f32_32x32x16_bf16 v[32:47], v[246:249], v[190:193], v[32:47]
	ds_read_b128 v[246:249], v194 offset:8192
	s_add_u32 m0, s33, 0x6000
	v_lshl_add_u64 v[10:11], v[10:11], 0, s[84:85]
	global_load_lds_dwordx4 v[10:11], off
	s_waitcnt lgkmcnt(4)
	v_mfma_f32_32x32x16_bf16 v[16:31], v[250:253], v[190:193], v[16:31]
	ds_read_b128 v[250:253], v194 offset:12288
	v_add_u32_e32 v195, 0xc000, v234
	ds_read_b128 v[190:193], v195 offset:32768
	v_add_u32_e32 v194, 0xc000, v184
	s_waitcnt lgkmcnt(4)
	v_mfma_f32_32x32x16_bf16 v[128:143], v[238:241], v[180:183], v[128:143]
	ds_read_b128 v[238:241], v194
	s_add_u32 m0, s33, 0x8000
	v_lshl_add_u64 v[4:5], v[4:5], 0, s[84:85]
	global_load_lds_dwordx4 v[4:5], off
	s_waitcnt lgkmcnt(4)
	v_mfma_f32_32x32x16_bf16 v[48:63], v[242:245], v[180:183], v[48:63]
	ds_read_b128 v[242:245], v194 offset:4096
	s_waitcnt lgkmcnt(4)
	v_mfma_f32_32x32x16_bf16 v[32:47], v[246:249], v[180:183], v[32:47]
	ds_read_b128 v[246:249], v194 offset:8192
	s_add_u32 m0, s33, 0xa000
	v_lshl_add_u64 v[12:13], v[12:13], 0, s[84:85]
	global_load_lds_dwordx4 v[12:13], off
	s_waitcnt lgkmcnt(4)
	v_mfma_f32_32x32x16_bf16 v[16:31], v[250:253], v[180:183], v[16:31]
	ds_read_b128 v[250:253], v194 offset:12288
	s_waitcnt lgkmcnt(3)
	v_mfma_f32_32x32x16_bf16 v[128:143], v[238:241], v[190:193], v[128:143]
	s_waitcnt lgkmcnt(2)
	v_mfma_f32_32x32x16_bf16 v[48:63], v[242:245], v[190:193], v[48:63]
	s_waitcnt lgkmcnt(1)
	v_mfma_f32_32x32x16_bf16 v[32:47], v[246:249], v[190:193], v[32:47]
	s_waitcnt lgkmcnt(0)
	v_mfma_f32_32x32x16_bf16 v[16:31], v[250:253], v[190:193], v[16:31]
	s_waitcnt vmcnt(6)
	s_barrier
; DI f32x16 mfma(bf16x8 a, bf16x8 b, f32x16 c) { return __builtin_amdgcn_mfma_f32_32x32x16_bf16(a, b, c, 0, 0, 0); }
;     ...
;   for (int kt = 0; kt < nk; ++kt) {
;     const char* cur = lds + (kt & 1) * DBUF;
;     if (kt + 1 < nk) DMA_ISSUE((kt + 1) & 1, kt + 1)
; #pragma unroll(NTB == 1 ? 2 : 4)
;     for (int s = 0; s < 4; ++s) {
;       const int ro = ((2 * s + hh) ^ xr) * 16;
;       bf16x8 bfr[NTB];
; #pragma unroll
;       for (int tb = 0; tb < NTB; ++tb) bfr[tb] = *(const bf16x8*)(cur + bbase + tb * 32 * DROW + ro);
; #pragma unroll
;       for (int fb = 0; fb < NFB; ++fb) {
;         const bf16x8 afr = *(const bf16x8*)(cur + abase + fb * 32 * DROW + ro);
; #pragma unroll
;         for (int tb = 0; tb < NTB; ++tb) acc[tb * NFB + fb] = mfma(afr, bfr[tb], acc[tb * NFB + fb]);
;       }
;     }
;     asm volatile("s_waitcnt vmcnt(0) lgkmcnt(0)" ::: "memory");
;     __builtin_amdgcn_s_barrier();
	v_add_u32_e32 v195, 0x18000, v186
	ds_read_b128 v[180:183], v195 offset:32768
	v_add_u32_e32 v194, 0x18000, v14
	ds_read_b128 v[238:241], v194
	ds_read_b128 v[242:245], v194 offset:4096
	ds_read_b128 v[246:249], v194 offset:8192
	ds_read_b128 v[250:253], v194 offset:12288
	v_add_u32_e32 v195, 0x18000, v189
	ds_read_b128 v[190:193], v195 offset:32768
	v_add_u32_e32 v194, 0x18000, v15
	s_waitcnt lgkmcnt(4)
	v_mfma_f32_32x32x16_bf16 v[128:143], v[238:241], v[180:183], v[128:143]
	ds_read_b128 v[238:241], v194
	s_add_u32 m0, s33, 0xc000
	v_lshl_add_u64 v[2:3], v[2:3], 0, s[84:85]
	global_load_lds_dwordx4 v[2:3], off
	s_waitcnt lgkmcnt(4)
	v_mfma_f32_32x32x16_bf16 v[48:63], v[242:245], v[180:183], v[48:63]
	ds_read_b128 v[242:245], v194 offset:4096
	s_waitcnt lgkmcnt(4)
	v_mfma_f32_32x32x16_bf16 v[32:47], v[246:249], v[180:183], v[32:47]
	ds_read_b128 v[246:249], v194 offset:8192
	s_add_u32 m0, s33, 0xe000
	v_lshl_add_u64 v[6:7], v[6:7], 0, s[84:85]
	global_load_lds_dwordx4 v[6:7], off
	s_waitcnt lgkmcnt(4)
	v_mfma_f32_32x32x16_bf16 v[16:31], v[250:253], v[180:183], v[16:31]
	ds_read_b128 v[250:253], v194 offset:12288
	v_add_u32_e32 v195, 0x18000, v233
	ds_read_b128 v[180:183], v195 offset:32768
	v_add_u32_e32 v194, 0x18000, v0
	s_waitcnt lgkmcnt(4)
	v_mfma_f32_32x32x16_bf16 v[128:143], v[238:241], v[190:193], v[128:143]
	ds_read_b128 v[238:241], v194
	s_add_u32 m0, s33, 0x10000
	v_lshl_add_u64 v[8:9], v[8:9], 0, s[84:85]
	global_load_lds_dwordx4 v[8:9], off
	s_waitcnt lgkmcnt(4)
	v_mfma_f32_32x32x16_bf16 v[48:63], v[242:245], v[190:193], v[48:63]
	ds_read_b128 v[242:245], v194 offset:4096
	s_waitcnt lgkmcnt(4)
	v_mfma_f32_32x32x16_bf16 v[32:47], v[246:249], v[190:193], v[32:47]
	ds_read_b128 v[246:249], v194 offset:8192
	s_add_u32 m0, s33, 0x12000
	v_lshl_add_u64 v[10:11], v[10:11], 0, s[84:85]
	global_load_lds_dwordx4 v[10:11], off
	s_waitcnt lgkmcnt(4)
	v_mfma_f32_32x32x16_bf16 v[16:31], v[250:253], v[190:193], v[16:31]
	ds_read_b128 v[250:253], v194 offset:12288
	v_add_u32_e32 v195, 0x18000, v234
	ds_read_b128 v[190:193], v195 offset:32768
	v_add_u32_e32 v194, 0x18000, v184
	s_waitcnt lgkmcnt(4)
	v_mfma_f32_32x32x16_bf16 v[128:143], v[238:241], v[180:183], v[128:143]
	ds_read_b128 v[238:241], v194
	s_add_u32 m0, s33, 0x14000
	v_lshl_add_u64 v[4:5], v[4:5], 0, s[84:85]
	global_load_lds_dwordx4 v[4:5], off
	s_waitcnt lgkmcnt(4)
	v_mfma_f32_32x32x16_bf16 v[48:63], v[242:245], v[180:183], v[48:63]
	ds_read_b128 v[242:245], v194 offset:4096
	s_waitcnt lgkmcnt(4)
	v_mfma_f32_32x32x16_bf16 v[32:47], v[246:249], v[180:183], v[32:47]
	ds_read_b128 v[246:249], v194 offset:8192
	s_add_u32 m0, s33, 0x16000
	v_lshl_add_u64 v[12:13], v[12:13], 0, s[84:85]
	global_load_lds_dwordx4 v[12:13], off
	s_waitcnt lgkmcnt(4)
	v_mfma_f32_32x32x16_bf16 v[16:31], v[250:253], v[180:183], v[16:31]
	ds_read_b128 v[250:253], v194 offset:12288
	s_waitcnt lgkmcnt(3)
	v_mfma_f32_32x32x16_bf16 v[128:143], v[238:241], v[190:193], v[128:143]
	s_waitcnt lgkmcnt(2)
	v_mfma_f32_32x32x16_bf16 v[48:63], v[242:245], v[190:193], v[48:63]
	s_waitcnt lgkmcnt(1)
	v_mfma_f32_32x32x16_bf16 v[32:47], v[246:249], v[190:193], v[32:47]
	s_waitcnt lgkmcnt(0)
	v_mfma_f32_32x32x16_bf16 v[16:31], v[250:253], v[190:193], v[16:31]
	s_waitcnt vmcnt(6)
	s_barrier
	ds_read_b128 v[180:183], v186 offset:32768
	ds_read_b128 v[238:241], v14
	ds_read_b128 v[242:245], v14 offset:4096
	ds_read_b128 v[246:249], v14 offset:8192
	ds_read_b128 v[250:253], v14 offset:12288
	ds_read_b128 v[190:193], v189 offset:32768
	s_waitcnt lgkmcnt(4)
	v_mfma_f32_32x32x16_bf16 v[128:143], v[238:241], v[180:183], v[128:143]
	ds_read_b128 v[238:241], v15
	s_add_u32 m0, s33, 0x18000
	v_lshl_add_u64 v[2:3], v[2:3], 0, s[84:85]
	global_load_lds_dwordx4 v[2:3], off
	s_waitcnt lgkmcnt(4)
	v_mfma_f32_32x32x16_bf16 v[48:63], v[242:245], v[180:183], v[48:63]
	ds_read_b128 v[242:245], v15 offset:4096
	s_waitcnt lgkmcnt(4)
	v_mfma_f32_32x32x16_bf16 v[32:47], v[246:249], v[180:183], v[32:47]
	ds_read_b128 v[246:249], v15 offset:8192
	s_add_u32 m0, s33, 0x1a000
	v_lshl_add_u64 v[6:7], v[6:7], 0, s[84:85]
	global_load_lds_dwordx4 v[6:7], off
	s_waitcnt lgkmcnt(4)
	v_mfma_f32_32x32x16_bf16 v[16:31], v[250:253], v[180:183], v[16:31]
	ds_read_b128 v[250:253], v15 offset:12288
	ds_read_b128 v[180:183], v233 offset:32768
	s_waitcnt lgkmcnt(4)
	v_mfma_f32_32x32x16_bf16 v[128:143], v[238:241], v[190:193], v[128:143]
	ds_read_b128 v[238:241], v0
	s_add_u32 m0, s33, 0x1c000
	v_lshl_add_u64 v[8:9], v[8:9], 0, s[84:85]
	global_load_lds_dwordx4 v[8:9], off
	s_waitcnt lgkmcnt(4)
	v_mfma_f32_32x32x16_bf16 v[48:63], v[242:245], v[190:193], v[48:63]
	ds_read_b128 v[242:245], v0 offset:4096
	s_waitcnt lgkmcnt(4)
	v_mfma_f32_32x32x16_bf16 v[32:47], v[246:249], v[190:193], v[32:47]
	ds_read_b128 v[246:249], v0 offset:8192
	s_add_u32 m0, s33, 0x1e000
	v_lshl_add_u64 v[10:11], v[10:11], 0, s[84:85]
	global_load_lds_dwordx4 v[10:11], off
	s_waitcnt lgkmcnt(4)
	v_mfma_f32_32x32x16_bf16 v[16:31], v[250:253], v[190:193], v[16:31]
	ds_read_b128 v[250:253], v0 offset:12288
	ds_read_b128 v[190:193], v234 offset:32768
	s_waitcnt lgkmcnt(4)
	v_mfma_f32_32x32x16_bf16 v[128:143], v[238:241], v[180:183], v[128:143]
	ds_read_b128 v[238:241], v184
	s_add_u32 m0, s33, 0x20000
	v_lshl_add_u64 v[4:5], v[4:5], 0, s[84:85]
	global_load_lds_dwordx4 v[4:5], off
	s_waitcnt lgkmcnt(4)
	v_mfma_f32_32x32x16_bf16 v[48:63], v[242:245], v[180:183], v[48:63]
	ds_read_b128 v[242:245], v184 offset:4096
	s_waitcnt lgkmcnt(4)
	v_mfma_f32_32x32x16_bf16 v[32:47], v[246:249], v[180:183], v[32:47]
	ds_read_b128 v[246:249], v184 offset:8192
	s_add_u32 m0, s33, 0x22000
	v_lshl_add_u64 v[12:13], v[12:13], 0, s[84:85]
	global_load_lds_dwordx4 v[12:13], off
	s_waitcnt lgkmcnt(4)
	v_mfma_f32_32x32x16_bf16 v[16:31], v[250:253], v[180:183], v[16:31]
	ds_read_b128 v[250:253], v184 offset:12288
	s_waitcnt lgkmcnt(3)
	v_mfma_f32_32x32x16_bf16 v[128:143], v[238:241], v[190:193], v[128:143]
	s_waitcnt lgkmcnt(2)
	v_mfma_f32_32x32x16_bf16 v[48:63], v[242:245], v[190:193], v[48:63]
	s_waitcnt lgkmcnt(1)
	v_mfma_f32_32x32x16_bf16 v[32:47], v[246:249], v[190:193], v[32:47]
	s_waitcnt lgkmcnt(0)
	v_mfma_f32_32x32x16_bf16 v[16:31], v[250:253], v[190:193], v[16:31]
	s_waitcnt vmcnt(6)
	s_barrier
; DI f32x16 mfma(bf16x8 a, bf16x8 b, f32x16 c) { return __builtin_amdgcn_mfma_f32_32x32x16_bf16(a, b, c, 0, 0, 0); }
;     ...
;   for (int kt = 0; kt < nk; ++kt) {
;     const char* cur = lds + (kt & 1) * DBUF;
;     if (kt + 1 < nk) DMA_ISSUE((kt + 1) & 1, kt + 1)
; #pragma unroll(NTB == 1 ? 2 : 4)
;     for (int s = 0; s < 4; ++s) {
;       const int ro = ((2 * s + hh) ^ xr) * 16;
;       bf16x8 bfr[NTB];
; #pragma unroll
;       for (int tb = 0; tb < NTB; ++tb) bfr[tb] = *(const bf16x8*)(cur + bbase + tb * 32 * DROW + ro);
; #pragma unroll
;       for (int fb = 0; fb < NFB; ++fb) {
;         const bf16x8 afr = *(const bf16x8*)(cur + abase + fb * 32 * DROW + ro);
; #pragma unroll
;         for (int tb = 0; tb < NTB; ++tb) acc[tb * NFB + fb] = mfma(afr, bfr[tb], acc[tb * NFB + fb]);
;       }
;     }
;     asm volatile("s_waitcnt vmcnt(0) lgkmcnt(0)" ::: "memory");
;     __builtin_amdgcn_s_barrier();
	v_add_u32_e32 v195, 0xc000, v186
	ds_read_b128 v[180:183], v195 offset:32768
	v_add_u32_e32 v194, 0xc000, v14
	ds_read_b128 v[238:241], v194
	ds_read_b128 v[242:245], v194 offset:4096
	ds_read_b128 v[246:249], v194 offset:8192
	ds_read_b128 v[250:253], v194 offset:12288
	v_add_u32_e32 v195, 0xc000, v189
	ds_read_b128 v[190:193], v195 offset:32768
	v_add_u32_e32 v194, 0xc000, v15
	s_waitcnt lgkmcnt(4)
	v_mfma_f32_32x32x16_bf16 v[128:143], v[238:241], v[180:183], v[128:143]
	ds_read_b128 v[238:241], v194
	s_add_u32 m0, s33, 0x0
	v_lshl_add_u64 v[2:3], v[2:3], 0, s[84:85]
	global_load_lds_dwordx4 v[2:3], off
	s_waitcnt lgkmcnt(4)
	v_mfma_f32_32x32x16_bf16 v[48:63], v[242:245], v[180:183], v[48:63]
	ds_read_b128 v[242:245], v194 offset:4096
	s_waitcnt lgkmcnt(4)
	v_mfma_f32_32x32x16_bf16 v[32:47], v[246:249], v[180:183], v[32:47]
	ds_read_b128 v[246:249], v194 offset:8192
	s_add_u32 m0, s33, 0x2000
	v_lshl_add_u64 v[6:7], v[6:7], 0, s[84:85]
	global_load_lds_dwordx4 v[6:7], off
	s_waitcnt lgkmcnt(4)
	v_mfma_f32_32x32x16_bf16 v[16:31], v[250:253], v[180:183], v[16:31]
	ds_read_b128 v[250:253], v194 offset:12288
	v_add_u32_e32 v195, 0xc000, v233
	ds_read_b128 v[180:183], v195 offset:32768
	v_add_u32_e32 v194, 0xc000, v0
	s_waitcnt lgkmcnt(4)
	v_mfma_f32_32x32x16_bf16 v[128:143], v[238:241], v[190:193], v[128:143]
	ds_read_b128 v[238:241], v194
	s_add_u32 m0, s33, 0x4000
	v_lshl_add_u64 v[8:9], v[8:9], 0, s[84:85]
	global_load_lds_dwordx4 v[8:9], off
	s_waitcnt lgkmcnt(4)
	v_mfma_f32_32x32x16_bf16 v[48:63], v[242:245], v[190:193], v[48:63]
	ds_read_b128 v[242:245], v194 offset:4096
	s_waitcnt lgkmcnt(4)
	v_mfma_f32_32x32x16_bf16 v[32:47], v[246:249], v[190:193], v[32:47]
	ds_read_b128 v[246:249], v194 offset:8192
	s_add_u32 m0, s33, 0x6000
	v_lshl_add_u64 v[10:11], v[10:11], 0, s[84:85]
	global_load_lds_dwordx4 v[10:11], off
	s_waitcnt lgkmcnt(4)
	v_mfma_f32_32x32x16_bf16 v[16:31], v[250:253], v[190:193], v[16:31]
	ds_read_b128 v[250:253], v194 offset:12288
	v_add_u32_e32 v195, 0xc000, v234
	ds_read_b128 v[190:193], v195 offset:32768
	v_add_u32_e32 v194, 0xc000, v184
	s_waitcnt lgkmcnt(4)
	v_mfma_f32_32x32x16_bf16 v[128:143], v[238:241], v[180:183], v[128:143]
	ds_read_b128 v[238:241], v194
	s_add_u32 m0, s33, 0x8000
	v_lshl_add_u64 v[4:5], v[4:5], 0, s[84:85]
	global_load_lds_dwordx4 v[4:5], off
	s_waitcnt lgkmcnt(4)
	v_mfma_f32_32x32x16_bf16 v[48:63], v[242:245], v[180:183], v[48:63]
	ds_read_b128 v[242:245], v194 offset:4096
	s_waitcnt lgkmcnt(4)
	v_mfma_f32_32x32x16_bf16 v[32:47], v[246:249], v[180:183], v[32:47]
	ds_read_b128 v[246:249], v194 offset:8192
	s_add_u32 m0, s33, 0xa000
	v_lshl_add_u64 v[12:13], v[12:13], 0, s[84:85]
	global_load_lds_dwordx4 v[12:13], off
	s_waitcnt lgkmcnt(4)
	v_mfma_f32_32x32x16_bf16 v[16:31], v[250:253], v[180:183], v[16:31]
	ds_read_b128 v[250:253], v194 offset:12288
	s_waitcnt lgkmcnt(3)
	v_mfma_f32_32x32x16_bf16 v[128:143], v[238:241], v[190:193], v[128:143]
	s_waitcnt lgkmcnt(2)
	v_mfma_f32_32x32x16_bf16 v[48:63], v[242:245], v[190:193], v[48:63]
	s_waitcnt lgkmcnt(1)
	v_mfma_f32_32x32x16_bf16 v[32:47], v[246:249], v[190:193], v[32:47]
	s_waitcnt lgkmcnt(0)
	v_mfma_f32_32x32x16_bf16 v[16:31], v[250:253], v[190:193], v[16:31]
	s_waitcnt vmcnt(6)
	s_barrier
	v_add_u32_e32 v195, 0x18000, v186
	ds_read_b128 v[180:183], v195 offset:32768
	v_add_u32_e32 v194, 0x18000, v14
	ds_read_b128 v[238:241], v194
	ds_read_b128 v[242:245], v194 offset:4096
	ds_read_b128 v[246:249], v194 offset:8192
	ds_read_b128 v[250:253], v194 offset:12288
	v_add_u32_e32 v195, 0x18000, v189
	ds_read_b128 v[190:193], v195 offset:32768
	v_add_u32_e32 v194, 0x18000, v15
	s_waitcnt lgkmcnt(4)
	v_mfma_f32_32x32x16_bf16 v[128:143], v[238:241], v[180:183], v[128:143]
	ds_read_b128 v[238:241], v194
	s_add_u32 m0, s33, 0xc000
	v_lshl_add_u64 v[2:3], v[2:3], 0, s[84:85]
	global_load_lds_dwordx4 v[2:3], off
	s_waitcnt lgkmcnt(4)
	v_mfma_f32_32x32x16_bf16 v[48:63], v[242:245], v[180:183], v[48:63]
	ds_read_b128 v[242:245], v194 offset:4096
	s_waitcnt lgkmcnt(4)
	v_mfma_f32_32x32x16_bf16 v[32:47], v[246:249], v[180:183], v[32:47]
	ds_read_b128 v[246:249], v194 offset:8192
	s_add_u32 m0, s33, 0xe000
	v_lshl_add_u64 v[6:7], v[6:7], 0, s[84:85]
	global_load_lds_dwordx4 v[6:7], off
	s_waitcnt lgkmcnt(4)
	v_mfma_f32_32x32x16_bf16 v[16:31], v[250:253], v[180:183], v[16:31]
	ds_read_b128 v[250:253], v194 offset:12288
	v_add_u32_e32 v195, 0x18000, v233
	ds_read_b128 v[180:183], v195 offset:32768
	v_add_u32_e32 v194, 0x18000, v0
	s_waitcnt lgkmcnt(4)
	v_mfma_f32_32x32x16_bf16 v[128:143], v[238:241], v[190:193], v[128:143]
	ds_read_b128 v[238:241], v194
	s_add_u32 m0, s33, 0x10000
	v_lshl_add_u64 v[8:9], v[8:9], 0, s[84:85]
	global_load_lds_dwordx4 v[8:9], off
	s_waitcnt lgkmcnt(4)
	v_mfma_f32_32x32x16_bf16 v[48:63], v[242:245], v[190:193], v[48:63]
	ds_read_b128 v[242:245], v194 offset:4096
	s_waitcnt lgkmcnt(4)
	v_mfma_f32_32x32x16_bf16 v[32:47], v[246:249], v[190:193], v[32:47]
	ds_read_b128 v[246:249], v194 offset:8192
	s_add_u32 m0, s33, 0x12000
	v_lshl_add_u64 v[10:11], v[10:11], 0, s[84:85]
	global_load_lds_dwordx4 v[10:11], off
	s_waitcnt lgkmcnt(4)
	v_mfma_f32_32x32x16_bf16 v[16:31], v[250:253], v[190:193], v[16:31]
	ds_read_b128 v[250:253], v194 offset:12288
	v_add_u32_e32 v195, 0x18000, v234
	ds_read_b128 v[190:193], v195 offset:32768
	v_add_u32_e32 v194, 0x18000, v184
	s_waitcnt lgkmcnt(4)
	v_mfma_f32_32x32x16_bf16 v[128:143], v[238:241], v[180:183], v[128:143]
	ds_read_b128 v[238:241], v194
	s_add_u32 m0, s33, 0x14000
	v_lshl_add_u64 v[4:5], v[4:5], 0, s[84:85]
	global_load_lds_dwordx4 v[4:5], off
	s_waitcnt lgkmcnt(4)
	v_mfma_f32_32x32x16_bf16 v[48:63], v[242:245], v[180:183], v[48:63]
	ds_read_b128 v[242:245], v194 offset:4096
	s_waitcnt lgkmcnt(4)
	v_mfma_f32_32x32x16_bf16 v[32:47], v[246:249], v[180:183], v[32:47]
	ds_read_b128 v[246:249], v194 offset:8192
	s_add_u32 m0, s33, 0x16000
	v_lshl_add_u64 v[12:13], v[12:13], 0, s[84:85]
	global_load_lds_dwordx4 v[12:13], off
	s_waitcnt lgkmcnt(4)
	v_mfma_f32_32x32x16_bf16 v[16:31], v[250:253], v[180:183], v[16:31]
	ds_read_b128 v[250:253], v194 offset:12288
	s_waitcnt lgkmcnt(3)
	v_mfma_f32_32x32x16_bf16 v[128:143], v[238:241], v[190:193], v[128:143]
	s_waitcnt lgkmcnt(2)
	v_mfma_f32_32x32x16_bf16 v[48:63], v[242:245], v[190:193], v[48:63]
	s_waitcnt lgkmcnt(1)
	v_mfma_f32_32x32x16_bf16 v[32:47], v[246:249], v[190:193], v[32:47]
	s_waitcnt lgkmcnt(0)
	v_mfma_f32_32x32x16_bf16 v[16:31], v[250:253], v[190:193], v[16:31]
	s_waitcnt vmcnt(6)
	s_barrier
; DI f32x16 mfma(bf16x8 a, bf16x8 b, f32x16 c) { return __builtin_amdgcn_mfma_f32_32x32x16_bf16(a, b, c, 0, 0, 0); }
;     ...
;   for (int kt = 0; kt < nk; ++kt) {
;     const char* cur = lds + (kt & 1) * DBUF;
;     if (kt + 1 < nk) DMA_ISSUE((kt + 1) & 1, kt + 1)
; #pragma unroll(NTB == 1 ? 2 : 4)
;     for (int s = 0; s < 4; ++s) {
;       const int ro = ((2 * s + hh) ^ xr) * 16;
;       bf16x8 bfr[NTB];
; #pragma unroll
;       for (int tb = 0; tb < NTB; ++tb) bfr[tb] = *(const bf16x8*)(cur + bbase + tb * 32 * DROW + ro);
; #pragma unroll
;       for (int fb = 0; fb < NFB; ++fb) {
;         const bf16x8 afr = *(const bf16x8*)(cur + abase + fb * 32 * DROW + ro);
; #pragma unroll
;         for (int tb = 0; tb < NTB; ++tb) acc[tb * NFB + fb] = mfma(afr, bfr[tb], acc[tb * NFB + fb]);
;       }
;     }
;     asm volatile("s_waitcnt vmcnt(0) lgkmcnt(0)" ::: "memory");
;     __builtin_amdgcn_s_barrier();
	ds_read_b128 v[180:183], v186 offset:32768
	ds_read_b128 v[238:241], v14
	ds_read_b128 v[242:245], v14 offset:4096
	ds_read_b128 v[246:249], v14 offset:8192
	ds_read_b128 v[250:253], v14 offset:12288
	ds_read_b128 v[190:193], v189 offset:32768
	s_waitcnt lgkmcnt(4)
	v_mfma_f32_32x32x16_bf16 v[128:143], v[238:241], v[180:183], v[128:143]
	ds_read_b128 v[238:241], v15
	s_add_u32 m0, s33, 0x18000
	v_lshl_add_u64 v[2:3], v[2:3], 0, s[84:85]
	global_load_lds_dwordx4 v[2:3], off
	s_waitcnt lgkmcnt(4)
	v_mfma_f32_32x32x16_bf16 v[48:63], v[242:245], v[180:183], v[48:63]
	ds_read_b128 v[242:245], v15 offset:4096
	s_waitcnt lgkmcnt(4)
	v_mfma_f32_32x32x16_bf16 v[32:47], v[246:249], v[180:183], v[32:47]
	ds_read_b128 v[246:249], v15 offset:8192
	s_add_u32 m0, s33, 0x1a000
	v_lshl_add_u64 v[6:7], v[6:7], 0, s[84:85]
	global_load_lds_dwordx4 v[6:7], off
	s_waitcnt lgkmcnt(4)
	v_mfma_f32_32x32x16_bf16 v[16:31], v[250:253], v[180:183], v[16:31]
	ds_read_b128 v[250:253], v15 offset:12288
	ds_read_b128 v[180:183], v233 offset:32768
	s_waitcnt lgkmcnt(4)
	v_mfma_f32_32x32x16_bf16 v[128:143], v[238:241], v[190:193], v[128:143]
	ds_read_b128 v[238:241], v0
	s_add_u32 m0, s33, 0x1c000
	v_lshl_add_u64 v[8:9], v[8:9], 0, s[84:85]
	global_load_lds_dwordx4 v[8:9], off
	s_waitcnt lgkmcnt(4)
	v_mfma_f32_32x32x16_bf16 v[48:63], v[242:245], v[190:193], v[48:63]
	ds_read_b128 v[242:245], v0 offset:4096
	s_waitcnt lgkmcnt(4)
	v_mfma_f32_32x32x16_bf16 v[32:47], v[246:249], v[190:193], v[32:47]
	ds_read_b128 v[246:249], v0 offset:8192
	s_add_u32 m0, s33, 0x1e000
	v_lshl_add_u64 v[10:11], v[10:11], 0, s[84:85]
	global_load_lds_dwordx4 v[10:11], off
	s_waitcnt lgkmcnt(4)
	v_mfma_f32_32x32x16_bf16 v[16:31], v[250:253], v[190:193], v[16:31]
	ds_read_b128 v[250:253], v0 offset:12288
	ds_read_b128 v[190:193], v234 offset:32768
	s_waitcnt lgkmcnt(4)
	v_mfma_f32_32x32x16_bf16 v[128:143], v[238:241], v[180:183], v[128:143]
	ds_read_b128 v[238:241], v184
	s_add_u32 m0, s33, 0x20000
	v_lshl_add_u64 v[4:5], v[4:5], 0, s[84:85]
	global_load_lds_dwordx4 v[4:5], off
	s_waitcnt lgkmcnt(4)
	v_mfma_f32_32x32x16_bf16 v[48:63], v[242:245], v[180:183], v[48:63]
	ds_read_b128 v[242:245], v184 offset:4096
	s_waitcnt lgkmcnt(4)
	v_mfma_f32_32x32x16_bf16 v[32:47], v[246:249], v[180:183], v[32:47]
	ds_read_b128 v[246:249], v184 offset:8192
	s_add_u32 m0, s33, 0x22000
	v_lshl_add_u64 v[12:13], v[12:13], 0, s[84:85]
	global_load_lds_dwordx4 v[12:13], off
	s_waitcnt lgkmcnt(4)
	v_mfma_f32_32x32x16_bf16 v[16:31], v[250:253], v[180:183], v[16:31]
	ds_read_b128 v[250:253], v184 offset:12288
	s_waitcnt lgkmcnt(3)
	v_mfma_f32_32x32x16_bf16 v[128:143], v[238:241], v[190:193], v[128:143]
	s_waitcnt lgkmcnt(2)
	v_mfma_f32_32x32x16_bf16 v[48:63], v[242:245], v[190:193], v[48:63]
	s_waitcnt lgkmcnt(1)
	v_mfma_f32_32x32x16_bf16 v[32:47], v[246:249], v[190:193], v[32:47]
	s_waitcnt lgkmcnt(0)
	v_mfma_f32_32x32x16_bf16 v[16:31], v[250:253], v[190:193], v[16:31]
	s_waitcnt vmcnt(6)
	s_barrier
	v_add_u32_e32 v195, 0xc000, v186
	ds_read_b128 v[180:183], v195 offset:32768
	v_add_u32_e32 v194, 0xc000, v14
	ds_read_b128 v[238:241], v194
	ds_read_b128 v[242:245], v194 offset:4096
	ds_read_b128 v[246:249], v194 offset:8192
	ds_read_b128 v[250:253], v194 offset:12288
	v_add_u32_e32 v195, 0xc000, v189
	ds_read_b128 v[190:193], v195 offset:32768
	v_add_u32_e32 v194, 0xc000, v15
	s_waitcnt lgkmcnt(4)
	v_mfma_f32_32x32x16_bf16 v[128:143], v[238:241], v[180:183], v[128:143]
	ds_read_b128 v[238:241], v194
	s_add_u32 m0, s33, 0x0
	v_lshl_add_u64 v[2:3], v[2:3], 0, s[84:85]
	global_load_lds_dwordx4 v[2:3], off
	s_waitcnt lgkmcnt(4)
	v_mfma_f32_32x32x16_bf16 v[48:63], v[242:245], v[180:183], v[48:63]
	ds_read_b128 v[242:245], v194 offset:4096
	s_waitcnt lgkmcnt(4)
	v_mfma_f32_32x32x16_bf16 v[32:47], v[246:249], v[180:183], v[32:47]
	ds_read_b128 v[246:249], v194 offset:8192
	s_add_u32 m0, s33, 0x2000
	v_lshl_add_u64 v[6:7], v[6:7], 0, s[84:85]
	global_load_lds_dwordx4 v[6:7], off
	s_waitcnt lgkmcnt(4)
	v_mfma_f32_32x32x16_bf16 v[16:31], v[250:253], v[180:183], v[16:31]
	ds_read_b128 v[250:253], v194 offset:12288
	v_add_u32_e32 v195, 0xc000, v233
	ds_read_b128 v[180:183], v195 offset:32768
	v_add_u32_e32 v194, 0xc000, v0
	s_waitcnt lgkmcnt(4)
	v_mfma_f32_32x32x16_bf16 v[128:143], v[238:241], v[190:193], v[128:143]
	ds_read_b128 v[238:241], v194
	s_add_u32 m0, s33, 0x4000
	v_lshl_add_u64 v[8:9], v[8:9], 0, s[84:85]
	global_load_lds_dwordx4 v[8:9], off
	s_waitcnt lgkmcnt(4)
	v_mfma_f32_32x32x16_bf16 v[48:63], v[242:245], v[190:193], v[48:63]
	ds_read_b128 v[242:245], v194 offset:4096
	s_waitcnt lgkmcnt(4)
	v_mfma_f32_32x32x16_bf16 v[32:47], v[246:249], v[190:193], v[32:47]
	ds_read_b128 v[246:249], v194 offset:8192
	s_add_u32 m0, s33, 0x6000
	v_lshl_add_u64 v[10:11], v[10:11], 0, s[84:85]
	global_load_lds_dwordx4 v[10:11], off
	s_waitcnt lgkmcnt(4)
	v_mfma_f32_32x32x16_bf16 v[16:31], v[250:253], v[190:193], v[16:31]
	ds_read_b128 v[250:253], v194 offset:12288
	v_add_u32_e32 v195, 0xc000, v234
	ds_read_b128 v[190:193], v195 offset:32768
	v_add_u32_e32 v194, 0xc000, v184
	s_waitcnt lgkmcnt(4)
	v_mfma_f32_32x32x16_bf16 v[128:143], v[238:241], v[180:183], v[128:143]
	ds_read_b128 v[238:241], v194
	s_add_u32 m0, s33, 0x8000
	v_lshl_add_u64 v[4:5], v[4:5], 0, s[84:85]
	global_load_lds_dwordx4 v[4:5], off
	s_waitcnt lgkmcnt(4)
	v_mfma_f32_32x32x16_bf16 v[48:63], v[242:245], v[180:183], v[48:63]
	ds_read_b128 v[242:245], v194 offset:4096
	s_waitcnt lgkmcnt(4)
	v_mfma_f32_32x32x16_bf16 v[32:47], v[246:249], v[180:183], v[32:47]
	ds_read_b128 v[246:249], v194 offset:8192
	s_add_u32 m0, s33, 0xa000
	v_lshl_add_u64 v[12:13], v[12:13], 0, s[84:85]
	global_load_lds_dwordx4 v[12:13], off
	s_waitcnt lgkmcnt(4)
	v_mfma_f32_32x32x16_bf16 v[16:31], v[250:253], v[180:183], v[16:31]
	ds_read_b128 v[250:253], v194 offset:12288
	s_waitcnt lgkmcnt(3)
	v_mfma_f32_32x32x16_bf16 v[128:143], v[238:241], v[190:193], v[128:143]
	s_waitcnt lgkmcnt(2)
	v_mfma_f32_32x32x16_bf16 v[48:63], v[242:245], v[190:193], v[48:63]
	s_waitcnt lgkmcnt(1)
	v_mfma_f32_32x32x16_bf16 v[32:47], v[246:249], v[190:193], v[32:47]
	s_waitcnt lgkmcnt(0)
	v_mfma_f32_32x32x16_bf16 v[16:31], v[250:253], v[190:193], v[16:31]
	s_waitcnt vmcnt(6)
	s_barrier
; DI f32x16 mfma(bf16x8 a, bf16x8 b, f32x16 c) { return __builtin_amdgcn_mfma_f32_32x32x16_bf16(a, b, c, 0, 0, 0); }
;     ...
;   for (int kt = 0; kt < nk; ++kt) {
;     const char* cur = lds + (kt & 1) * DBUF;
;     if (kt + 1 < nk) DMA_ISSUE((kt + 1) & 1, kt + 1)
; #pragma unroll(NTB == 1 ? 2 : 4)
;     for (int s = 0; s < 4; ++s) {
;       const int ro = ((2 * s + hh) ^ xr) * 16;
;       bf16x8 bfr[NTB];
; #pragma unroll
;       for (int tb = 0; tb < NTB; ++tb) bfr[tb] = *(const bf16x8*)(cur + bbase + tb * 32 * DROW + ro);
; #pragma unroll
;       for (int fb = 0; fb < NFB; ++fb) {
;         const bf16x8 afr = *(const bf16x8*)(cur + abase + fb * 32 * DROW + ro);
; #pragma unroll
;         for (int tb = 0; tb < NTB; ++tb) acc[tb * NFB + fb] = mfma(afr, bfr[tb], acc[tb * NFB + fb]);
;       }
;     }
;     asm volatile("s_waitcnt vmcnt(0) lgkmcnt(0)" ::: "memory");
;     __builtin_amdgcn_s_barrier();
	v_add_u32_e32 v195, 0x18000, v186
	ds_read_b128 v[180:183], v195 offset:32768
	v_add_u32_e32 v194, 0x18000, v14
	ds_read_b128 v[238:241], v194
	ds_read_b128 v[242:245], v194 offset:4096
	ds_read_b128 v[246:249], v194 offset:8192
	ds_read_b128 v[250:253], v194 offset:12288
	v_add_u32_e32 v195, 0x18000, v189
	ds_read_b128 v[190:193], v195 offset:32768
	v_add_u32_e32 v194, 0x18000, v15
	s_waitcnt lgkmcnt(4)
	v_mfma_f32_32x32x16_bf16 v[128:143], v[238:241], v[180:183], v[128:143]
	ds_read_b128 v[238:241], v194
	s_add_u32 m0, s33, 0xc000
	v_lshl_add_u64 v[2:3], v[2:3], 0, s[84:85]
	global_load_lds_dwordx4 v[2:3], off
	s_waitcnt lgkmcnt(4)
	v_mfma_f32_32x32x16_bf16 v[48:63], v[242:245], v[180:183], v[48:63]
	ds_read_b128 v[242:245], v194 offset:4096
	s_waitcnt lgkmcnt(4)
	v_mfma_f32_32x32x16_bf16 v[32:47], v[246:249], v[180:183], v[32:47]
	ds_read_b128 v[246:249], v194 offset:8192
	s_add_u32 m0, s33, 0xe000
	v_lshl_add_u64 v[6:7], v[6:7], 0, s[84:85]
	global_load_lds_dwordx4 v[6:7], off
	s_waitcnt lgkmcnt(4)
	v_mfma_f32_32x32x16_bf16 v[16:31], v[250:253], v[180:183], v[16:31]
	ds_read_b128 v[250:253], v194 offset:12288
	v_add_u32_e32 v195, 0x18000, v233
	ds_read_b128 v[180:183], v195 offset:32768
	v_add_u32_e32 v194, 0x18000, v0
	s_waitcnt lgkmcnt(4)
	v_mfma_f32_32x32x16_bf16 v[128:143], v[238:241], v[190:193], v[128:143]
	ds_read_b128 v[238:241], v194
	s_add_u32 m0, s33, 0x10000
	v_lshl_add_u64 v[8:9], v[8:9], 0, s[84:85]
	global_load_lds_dwordx4 v[8:9], off
	s_waitcnt lgkmcnt(4)
	v_mfma_f32_32x32x16_bf16 v[48:63], v[242:245], v[190:193], v[48:63]
	ds_read_b128 v[242:245], v194 offset:4096
	s_waitcnt lgkmcnt(4)
	v_mfma_f32_32x32x16_bf16 v[32:47], v[246:249], v[190:193], v[32:47]
	ds_read_b128 v[246:249], v194 offset:8192
	s_add_u32 m0, s33, 0x12000
	v_lshl_add_u64 v[10:11], v[10:11], 0, s[84:85]
	global_load_lds_dwordx4 v[10:11], off
	s_waitcnt lgkmcnt(4)
	v_mfma_f32_32x32x16_bf16 v[16:31], v[250:253], v[190:193], v[16:31]
	ds_read_b128 v[250:253], v194 offset:12288
	v_add_u32_e32 v195, 0x18000, v234
	ds_read_b128 v[190:193], v195 offset:32768
	v_add_u32_e32 v194, 0x18000, v184
	s_waitcnt lgkmcnt(4)
	v_mfma_f32_32x32x16_bf16 v[128:143], v[238:241], v[180:183], v[128:143]
	ds_read_b128 v[238:241], v194
	s_add_u32 m0, s33, 0x14000
	v_lshl_add_u64 v[4:5], v[4:5], 0, s[84:85]
	global_load_lds_dwordx4 v[4:5], off
	s_waitcnt lgkmcnt(4)
	v_mfma_f32_32x32x16_bf16 v[48:63], v[242:245], v[180:183], v[48:63]
	ds_read_b128 v[242:245], v194 offset:4096
	s_waitcnt lgkmcnt(4)
	v_mfma_f32_32x32x16_bf16 v[32:47], v[246:249], v[180:183], v[32:47]
	ds_read_b128 v[246:249], v194 offset:8192
	s_add_u32 m0, s33, 0x16000
	v_lshl_add_u64 v[12:13], v[12:13], 0, s[84:85]
	global_load_lds_dwordx4 v[12:13], off
	s_waitcnt lgkmcnt(4)
	v_mfma_f32_32x32x16_bf16 v[16:31], v[250:253], v[180:183], v[16:31]
	ds_read_b128 v[250:253], v194 offset:12288
	s_waitcnt lgkmcnt(3)
	v_mfma_f32_32x32x16_bf16 v[128:143], v[238:241], v[190:193], v[128:143]
	s_waitcnt lgkmcnt(2)
	v_mfma_f32_32x32x16_bf16 v[48:63], v[242:245], v[190:193], v[48:63]
	s_waitcnt lgkmcnt(1)
	v_mfma_f32_32x32x16_bf16 v[32:47], v[246:249], v[190:193], v[32:47]
	s_waitcnt lgkmcnt(0)
	v_mfma_f32_32x32x16_bf16 v[16:31], v[250:253], v[190:193], v[16:31]
	s_waitcnt vmcnt(6)
	s_barrier
	ds_read_b128 v[180:183], v186 offset:32768
	ds_read_b128 v[238:241], v14
	ds_read_b128 v[242:245], v14 offset:4096
	ds_read_b128 v[246:249], v14 offset:8192
	ds_read_b128 v[250:253], v14 offset:12288
	ds_read_b128 v[190:193], v189 offset:32768
	s_waitcnt lgkmcnt(4)
	v_mfma_f32_32x32x16_bf16 v[128:143], v[238:241], v[180:183], v[128:143]
	ds_read_b128 v[238:241], v15
	s_add_u32 m0, s33, 0x18000
	v_lshl_add_u64 v[2:3], v[2:3], 0, s[84:85]
	global_load_lds_dwordx4 v[2:3], off
	s_waitcnt lgkmcnt(4)
	v_mfma_f32_32x32x16_bf16 v[48:63], v[242:245], v[180:183], v[48:63]
	ds_read_b128 v[242:245], v15 offset:4096
	s_waitcnt lgkmcnt(4)
	v_mfma_f32_32x32x16_bf16 v[32:47], v[246:249], v[180:183], v[32:47]
	ds_read_b128 v[246:249], v15 offset:8192
	s_add_u32 m0, s33, 0x1a000
	v_lshl_add_u64 v[6:7], v[6:7], 0, s[84:85]
	global_load_lds_dwordx4 v[6:7], off
	s_waitcnt lgkmcnt(4)
	v_mfma_f32_32x32x16_bf16 v[16:31], v[250:253], v[180:183], v[16:31]
	ds_read_b128 v[250:253], v15 offset:12288
	ds_read_b128 v[180:183], v233 offset:32768
	s_waitcnt lgkmcnt(4)
	v_mfma_f32_32x32x16_bf16 v[128:143], v[238:241], v[190:193], v[128:143]
	ds_read_b128 v[238:241], v0
	s_add_u32 m0, s33, 0x1c000
	v_lshl_add_u64 v[8:9], v[8:9], 0, s[84:85]
	global_load_lds_dwordx4 v[8:9], off
	s_waitcnt lgkmcnt(4)
	v_mfma_f32_32x32x16_bf16 v[48:63], v[242:245], v[190:193], v[48:63]
	ds_read_b128 v[242:245], v0 offset:4096
	s_waitcnt lgkmcnt(4)
	v_mfma_f32_32x32x16_bf16 v[32:47], v[246:249], v[190:193], v[32:47]
	ds_read_b128 v[246:249], v0 offset:8192
	s_add_u32 m0, s33, 0x1e000
	v_lshl_add_u64 v[10:11], v[10:11], 0, s[84:85]
	global_load_lds_dwordx4 v[10:11], off
	s_waitcnt lgkmcnt(4)
	v_mfma_f32_32x32x16_bf16 v[16:31], v[250:253], v[190:193], v[16:31]
	ds_read_b128 v[250:253], v0 offset:12288
	ds_read_b128 v[190:193], v234 offset:32768
	s_waitcnt lgkmcnt(4)
	v_mfma_f32_32x32x16_bf16 v[128:143], v[238:241], v[180:183], v[128:143]
	ds_read_b128 v[238:241], v184
	s_add_u32 m0, s33, 0x20000
	v_lshl_add_u64 v[4:5], v[4:5], 0, s[84:85]
	global_load_lds_dwordx4 v[4:5], off
	s_waitcnt lgkmcnt(4)
	v_mfma_f32_32x32x16_bf16 v[48:63], v[242:245], v[180:183], v[48:63]
	ds_read_b128 v[242:245], v184 offset:4096
	s_waitcnt lgkmcnt(4)
	v_mfma_f32_32x32x16_bf16 v[32:47], v[246:249], v[180:183], v[32:47]
	ds_read_b128 v[246:249], v184 offset:8192
	s_add_u32 m0, s33, 0x22000
	v_lshl_add_u64 v[12:13], v[12:13], 0, s[84:85]
	global_load_lds_dwordx4 v[12:13], off
	s_waitcnt lgkmcnt(4)
	v_mfma_f32_32x32x16_bf16 v[16:31], v[250:253], v[180:183], v[16:31]
	ds_read_b128 v[250:253], v184 offset:12288
	s_waitcnt lgkmcnt(3)
	v_mfma_f32_32x32x16_bf16 v[128:143], v[238:241], v[190:193], v[128:143]
	s_waitcnt lgkmcnt(2)
	v_mfma_f32_32x32x16_bf16 v[48:63], v[242:245], v[190:193], v[48:63]
	s_waitcnt lgkmcnt(1)
	v_mfma_f32_32x32x16_bf16 v[32:47], v[246:249], v[190:193], v[32:47]
	s_waitcnt lgkmcnt(0)
	v_mfma_f32_32x32x16_bf16 v[16:31], v[250:253], v[190:193], v[16:31]
	s_waitcnt vmcnt(6)
	s_barrier
; DI f32x16 mfma(bf16x8 a, bf16x8 b, f32x16 c) { return __builtin_amdgcn_mfma_f32_32x32x16_bf16(a, b, c, 0, 0, 0); }
;     ...
;   for (int kt = 0; kt < nk; ++kt) {
;     const char* cur = lds + (kt & 1) * DBUF;
;     if (kt + 1 < nk) DMA_ISSUE((kt + 1) & 1, kt + 1)
; #pragma unroll(NTB == 1 ? 2 : 4)
;     for (int s = 0; s < 4; ++s) {
;       const int ro = ((2 * s + hh) ^ xr) * 16;
;       bf16x8 bfr[NTB];
; #pragma unroll
;       for (int tb = 0; tb < NTB; ++tb) bfr[tb] = *(const bf16x8*)(cur + bbase + tb * 32 * DROW + ro);
; #pragma unroll
;       for (int fb = 0; fb < NFB; ++fb) {
;         const bf16x8 afr = *(const bf16x8*)(cur + abase + fb * 32 * DROW + ro);
; #pragma unroll
;         for (int tb = 0; tb < NTB; ++tb) acc[tb * NFB + fb] = mfma(afr, bfr[tb], acc[tb * NFB + fb]);
;       }
;     }
;     asm volatile("s_waitcnt vmcnt(0) lgkmcnt(0)" ::: "memory");
;     __builtin_amdgcn_s_barrier();
	v_add_u32_e32 v195, 0xc000, v186
	ds_read_b128 v[180:183], v195 offset:32768
	v_add_u32_e32 v194, 0xc000, v14
	ds_read_b128 v[238:241], v194
	ds_read_b128 v[242:245], v194 offset:4096
	ds_read_b128 v[246:249], v194 offset:8192
	ds_read_b128 v[250:253], v194 offset:12288
	v_add_u32_e32 v195, 0xc000, v189
	ds_read_b128 v[190:193], v195 offset:32768
	v_add_u32_e32 v194, 0xc000, v15
	s_waitcnt lgkmcnt(4)
	v_mfma_f32_32x32x16_bf16 v[128:143], v[238:241], v[180:183], v[128:143]
	ds_read_b128 v[238:241], v194
	s_add_u32 m0, s33, 0x0
	v_lshl_add_u64 v[2:3], v[2:3], 0, s[84:85]
	global_load_lds_dwordx4 v[2:3], off
	s_waitcnt lgkmcnt(4)
	v_mfma_f32_32x32x16_bf16 v[48:63], v[242:245], v[180:183], v[48:63]
	ds_read_b128 v[242:245], v194 offset:4096
	s_waitcnt lgkmcnt(4)
	v_mfma_f32_32x32x16_bf16 v[32:47], v[246:249], v[180:183], v[32:47]
	ds_read_b128 v[246:249], v194 offset:8192
	s_add_u32 m0, s33, 0x2000
	v_lshl_add_u64 v[6:7], v[6:7], 0, s[84:85]
	global_load_lds_dwordx4 v[6:7], off
	s_waitcnt lgkmcnt(4)
	v_mfma_f32_32x32x16_bf16 v[16:31], v[250:253], v[180:183], v[16:31]
	ds_read_b128 v[250:253], v194 offset:12288
	v_add_u32_e32 v195, 0xc000, v233
	ds_read_b128 v[180:183], v195 offset:32768
	v_add_u32_e32 v194, 0xc000, v0
	s_waitcnt lgkmcnt(4)
	v_mfma_f32_32x32x16_bf16 v[128:143], v[238:241], v[190:193], v[128:143]
	ds_read_b128 v[238:241], v194
	s_add_u32 m0, s33, 0x4000
	v_lshl_add_u64 v[8:9], v[8:9], 0, s[84:85]
	global_load_lds_dwordx4 v[8:9], off
	s_waitcnt lgkmcnt(4)
	v_mfma_f32_32x32x16_bf16 v[48:63], v[242:245], v[190:193], v[48:63]
	ds_read_b128 v[242:245], v194 offset:4096
	s_waitcnt lgkmcnt(4)
	v_mfma_f32_32x32x16_bf16 v[32:47], v[246:249], v[190:193], v[32:47]
	ds_read_b128 v[246:249], v194 offset:8192
	s_add_u32 m0, s33, 0x6000
	v_lshl_add_u64 v[10:11], v[10:11], 0, s[84:85]
	global_load_lds_dwordx4 v[10:11], off
	s_waitcnt lgkmcnt(4)
	v_mfma_f32_32x32x16_bf16 v[16:31], v[250:253], v[190:193], v[16:31]
	ds_read_b128 v[250:253], v194 offset:12288
	v_add_u32_e32 v195, 0xc000, v234
	ds_read_b128 v[190:193], v195 offset:32768
	v_add_u32_e32 v194, 0xc000, v184
	s_waitcnt lgkmcnt(4)
	v_mfma_f32_32x32x16_bf16 v[128:143], v[238:241], v[180:183], v[128:143]
	ds_read_b128 v[238:241], v194
	s_add_u32 m0, s33, 0x8000
	v_lshl_add_u64 v[4:5], v[4:5], 0, s[84:85]
	global_load_lds_dwordx4 v[4:5], off
	s_waitcnt lgkmcnt(4)
	v_mfma_f32_32x32x16_bf16 v[48:63], v[242:245], v[180:183], v[48:63]
	ds_read_b128 v[242:245], v194 offset:4096
	s_waitcnt lgkmcnt(4)
	v_mfma_f32_32x32x16_bf16 v[32:47], v[246:249], v[180:183], v[32:47]
	ds_read_b128 v[246:249], v194 offset:8192
	s_add_u32 m0, s33, 0xa000
	v_lshl_add_u64 v[12:13], v[12:13], 0, s[84:85]
	global_load_lds_dwordx4 v[12:13], off
	s_waitcnt lgkmcnt(4)
	v_mfma_f32_32x32x16_bf16 v[16:31], v[250:253], v[180:183], v[16:31]
	ds_read_b128 v[250:253], v194 offset:12288
	s_waitcnt lgkmcnt(3)
	v_mfma_f32_32x32x16_bf16 v[128:143], v[238:241], v[190:193], v[128:143]
	s_waitcnt lgkmcnt(2)
	v_mfma_f32_32x32x16_bf16 v[48:63], v[242:245], v[190:193], v[48:63]
	s_waitcnt lgkmcnt(1)
	v_mfma_f32_32x32x16_bf16 v[32:47], v[246:249], v[190:193], v[32:47]
	s_waitcnt lgkmcnt(0)
	v_mfma_f32_32x32x16_bf16 v[16:31], v[250:253], v[190:193], v[16:31]
	s_waitcnt vmcnt(6)
	s_barrier
	v_add_u32_e32 v195, 0x18000, v186
	ds_read_b128 v[180:183], v195 offset:32768
	v_add_u32_e32 v194, 0x18000, v14
	ds_read_b128 v[238:241], v194
	ds_read_b128 v[242:245], v194 offset:4096
	ds_read_b128 v[246:249], v194 offset:8192
	ds_read_b128 v[250:253], v194 offset:12288
	v_add_u32_e32 v195, 0x18000, v189
	ds_read_b128 v[190:193], v195 offset:32768
	v_add_u32_e32 v194, 0x18000, v15
	s_waitcnt lgkmcnt(4)
	v_mfma_f32_32x32x16_bf16 v[128:143], v[238:241], v[180:183], v[128:143]
	ds_read_b128 v[238:241], v194
	s_add_u32 m0, s33, 0xc000
	v_lshl_add_u64 v[2:3], v[2:3], 0, s[84:85]
	global_load_lds_dwordx4 v[2:3], off
	s_waitcnt lgkmcnt(4)
	v_mfma_f32_32x32x16_bf16 v[48:63], v[242:245], v[180:183], v[48:63]
	ds_read_b128 v[242:245], v194 offset:4096
	s_waitcnt lgkmcnt(4)
	v_mfma_f32_32x32x16_bf16 v[32:47], v[246:249], v[180:183], v[32:47]
	ds_read_b128 v[246:249], v194 offset:8192
	s_add_u32 m0, s33, 0xe000
	v_lshl_add_u64 v[6:7], v[6:7], 0, s[84:85]
	global_load_lds_dwordx4 v[6:7], off
	s_waitcnt lgkmcnt(4)
	v_mfma_f32_32x32x16_bf16 v[16:31], v[250:253], v[180:183], v[16:31]
	ds_read_b128 v[250:253], v194 offset:12288
	v_add_u32_e32 v195, 0x18000, v233
	ds_read_b128 v[180:183], v195 offset:32768
	v_add_u32_e32 v194, 0x18000, v0
	s_waitcnt lgkmcnt(4)
	v_mfma_f32_32x32x16_bf16 v[128:143], v[238:241], v[190:193], v[128:143]
	ds_read_b128 v[238:241], v194
	s_add_u32 m0, s33, 0x10000
	v_lshl_add_u64 v[8:9], v[8:9], 0, s[84:85]
	global_load_lds_dwordx4 v[8:9], off
	s_waitcnt lgkmcnt(4)
	v_mfma_f32_32x32x16_bf16 v[48:63], v[242:245], v[190:193], v[48:63]
	ds_read_b128 v[242:245], v194 offset:4096
	s_waitcnt lgkmcnt(4)
	v_mfma_f32_32x32x16_bf16 v[32:47], v[246:249], v[190:193], v[32:47]
	ds_read_b128 v[246:249], v194 offset:8192
	s_add_u32 m0, s33, 0x12000
	v_lshl_add_u64 v[10:11], v[10:11], 0, s[84:85]
	global_load_lds_dwordx4 v[10:11], off
	s_waitcnt lgkmcnt(4)
	v_mfma_f32_32x32x16_bf16 v[16:31], v[250:253], v[190:193], v[16:31]
	ds_read_b128 v[250:253], v194 offset:12288
	v_add_u32_e32 v195, 0x18000, v234
	ds_read_b128 v[190:193], v195 offset:32768
	v_add_u32_e32 v194, 0x18000, v184
	s_waitcnt lgkmcnt(4)
	v_mfma_f32_32x32x16_bf16 v[128:143], v[238:241], v[180:183], v[128:143]
	ds_read_b128 v[238:241], v194
	s_add_u32 m0, s33, 0x14000
	v_lshl_add_u64 v[4:5], v[4:5], 0, s[84:85]
	global_load_lds_dwordx4 v[4:5], off
	s_waitcnt lgkmcnt(4)
	v_mfma_f32_32x32x16_bf16 v[48:63], v[242:245], v[180:183], v[48:63]
	ds_read_b128 v[242:245], v194 offset:4096
	s_waitcnt lgkmcnt(4)
	v_mfma_f32_32x32x16_bf16 v[32:47], v[246:249], v[180:183], v[32:47]
	ds_read_b128 v[246:249], v194 offset:8192
	s_add_u32 m0, s33, 0x16000
	v_lshl_add_u64 v[12:13], v[12:13], 0, s[84:85]
	global_load_lds_dwordx4 v[12:13], off
	s_waitcnt lgkmcnt(4)
	v_mfma_f32_32x32x16_bf16 v[16:31], v[250:253], v[180:183], v[16:31]
	ds_read_b128 v[250:253], v194 offset:12288
	s_waitcnt lgkmcnt(3)
	v_mfma_f32_32x32x16_bf16 v[128:143], v[238:241], v[190:193], v[128:143]
	s_waitcnt lgkmcnt(2)
	v_mfma_f32_32x32x16_bf16 v[48:63], v[242:245], v[190:193], v[48:63]
	s_waitcnt lgkmcnt(1)
	v_mfma_f32_32x32x16_bf16 v[32:47], v[246:249], v[190:193], v[32:47]
	s_waitcnt lgkmcnt(0)
	v_mfma_f32_32x32x16_bf16 v[16:31], v[250:253], v[190:193], v[16:31]
	s_waitcnt vmcnt(6)
	s_barrier
; DI f32x16 mfma(bf16x8 a, bf16x8 b, f32x16 c) { return __builtin_amdgcn_mfma_f32_32x32x16_bf16(a, b, c, 0, 0, 0); }
;     ...
;   for (int kt = 0; kt < nk; ++kt) {
;     const char* cur = lds + (kt & 1) * DBUF;
;     if (kt + 1 < nk) DMA_ISSUE((kt + 1) & 1, kt + 1)
; #pragma unroll(NTB == 1 ? 2 : 4)
;     for (int s = 0; s < 4; ++s) {
;       const int ro = ((2 * s + hh) ^ xr) * 16;
;       bf16x8 bfr[NTB];
; #pragma unroll
;       for (int tb = 0; tb < NTB; ++tb) bfr[tb] = *(const bf16x8*)(cur + bbase + tb * 32 * DROW + ro);
; #pragma unroll
;       for (int fb = 0; fb < NFB; ++fb) {
;         const bf16x8 afr = *(const bf16x8*)(cur + abase + fb * 32 * DROW + ro);
; #pragma unroll
;         for (int tb = 0; tb < NTB; ++tb) acc[tb * NFB + fb] = mfma(afr, bfr[tb], acc[tb * NFB + fb]);
;       }
;     }
;     asm volatile("s_waitcnt vmcnt(0) lgkmcnt(0)" ::: "memory");
;     __builtin_amdgcn_s_barrier();
	ds_read_b128 v[180:183], v186 offset:32768
	ds_read_b128 v[238:241], v14
	ds_read_b128 v[242:245], v14 offset:4096
	ds_read_b128 v[246:249], v14 offset:8192
	ds_read_b128 v[250:253], v14 offset:12288
	ds_read_b128 v[190:193], v189 offset:32768
	s_waitcnt lgkmcnt(4)
	v_mfma_f32_32x32x16_bf16 v[128:143], v[238:241], v[180:183], v[128:143]
	ds_read_b128 v[238:241], v15
	s_add_u32 m0, s33, 0x18000
	v_lshl_add_u64 v[2:3], v[2:3], 0, s[84:85]
	global_load_lds_dwordx4 v[2:3], off
	s_waitcnt lgkmcnt(4)
	v_mfma_f32_32x32x16_bf16 v[48:63], v[242:245], v[180:183], v[48:63]
	ds_read_b128 v[242:245], v15 offset:4096
	s_waitcnt lgkmcnt(4)
	v_mfma_f32_32x32x16_bf16 v[32:47], v[246:249], v[180:183], v[32:47]
	ds_read_b128 v[246:249], v15 offset:8192
	s_add_u32 m0, s33, 0x1a000
	v_lshl_add_u64 v[6:7], v[6:7], 0, s[84:85]
	global_load_lds_dwordx4 v[6:7], off
	s_waitcnt lgkmcnt(4)
	v_mfma_f32_32x32x16_bf16 v[16:31], v[250:253], v[180:183], v[16:31]
	ds_read_b128 v[250:253], v15 offset:12288
	ds_read_b128 v[180:183], v233 offset:32768
	s_waitcnt lgkmcnt(4)
	v_mfma_f32_32x32x16_bf16 v[128:143], v[238:241], v[190:193], v[128:143]
	ds_read_b128 v[238:241], v0
	s_add_u32 m0, s33, 0x1c000
	v_lshl_add_u64 v[8:9], v[8:9], 0, s[84:85]
	global_load_lds_dwordx4 v[8:9], off
	s_waitcnt lgkmcnt(4)
	v_mfma_f32_32x32x16_bf16 v[48:63], v[242:245], v[190:193], v[48:63]
	ds_read_b128 v[242:245], v0 offset:4096
	s_waitcnt lgkmcnt(4)
	v_mfma_f32_32x32x16_bf16 v[32:47], v[246:249], v[190:193], v[32:47]
	ds_read_b128 v[246:249], v0 offset:8192
	s_add_u32 m0, s33, 0x1e000
	v_lshl_add_u64 v[10:11], v[10:11], 0, s[84:85]
	global_load_lds_dwordx4 v[10:11], off
	s_waitcnt lgkmcnt(4)
	v_mfma_f32_32x32x16_bf16 v[16:31], v[250:253], v[190:193], v[16:31]
	ds_read_b128 v[250:253], v0 offset:12288
	ds_read_b128 v[190:193], v234 offset:32768
	s_waitcnt lgkmcnt(4)
	v_mfma_f32_32x32x16_bf16 v[128:143], v[238:241], v[180:183], v[128:143]
	ds_read_b128 v[238:241], v184
	s_add_u32 m0, s33, 0x20000
	v_lshl_add_u64 v[4:5], v[4:5], 0, s[84:85]
	global_load_lds_dwordx4 v[4:5], off
	s_waitcnt lgkmcnt(4)
	v_mfma_f32_32x32x16_bf16 v[48:63], v[242:245], v[180:183], v[48:63]
	ds_read_b128 v[242:245], v184 offset:4096
	s_waitcnt lgkmcnt(4)
	v_mfma_f32_32x32x16_bf16 v[32:47], v[246:249], v[180:183], v[32:47]
	ds_read_b128 v[246:249], v184 offset:8192
	s_add_u32 m0, s33, 0x22000
	v_lshl_add_u64 v[12:13], v[12:13], 0, s[84:85]
	global_load_lds_dwordx4 v[12:13], off
	s_waitcnt lgkmcnt(4)
	v_mfma_f32_32x32x16_bf16 v[16:31], v[250:253], v[180:183], v[16:31]
	ds_read_b128 v[250:253], v184 offset:12288
	s_waitcnt lgkmcnt(3)
	v_mfma_f32_32x32x16_bf16 v[128:143], v[238:241], v[190:193], v[128:143]
	s_waitcnt lgkmcnt(2)
	v_mfma_f32_32x32x16_bf16 v[48:63], v[242:245], v[190:193], v[48:63]
	s_waitcnt lgkmcnt(1)
	v_mfma_f32_32x32x16_bf16 v[32:47], v[246:249], v[190:193], v[32:47]
	s_waitcnt lgkmcnt(0)
	v_mfma_f32_32x32x16_bf16 v[16:31], v[250:253], v[190:193], v[16:31]
	s_waitcnt vmcnt(6)
	s_barrier
	v_add_u32_e32 v195, 0xc000, v186
	ds_read_b128 v[180:183], v195 offset:32768
	v_add_u32_e32 v194, 0xc000, v14
	ds_read_b128 v[238:241], v194
	ds_read_b128 v[242:245], v194 offset:4096
	ds_read_b128 v[246:249], v194 offset:8192
	ds_read_b128 v[250:253], v194 offset:12288
	v_add_u32_e32 v195, 0xc000, v189
	ds_read_b128 v[190:193], v195 offset:32768
	v_add_u32_e32 v194, 0xc000, v15
	s_waitcnt lgkmcnt(4)
	v_mfma_f32_32x32x16_bf16 v[128:143], v[238:241], v[180:183], v[128:143]
	ds_read_b128 v[238:241], v194
	s_waitcnt lgkmcnt(4)
	v_mfma_f32_32x32x16_bf16 v[48:63], v[242:245], v[180:183], v[48:63]
	ds_read_b128 v[242:245], v194 offset:4096
	s_waitcnt lgkmcnt(4)
	v_mfma_f32_32x32x16_bf16 v[32:47], v[246:249], v[180:183], v[32:47]
	ds_read_b128 v[246:249], v194 offset:8192
	s_waitcnt lgkmcnt(4)
	v_mfma_f32_32x32x16_bf16 v[16:31], v[250:253], v[180:183], v[16:31]
	ds_read_b128 v[250:253], v194 offset:12288
	v_add_u32_e32 v195, 0xc000, v233
	ds_read_b128 v[180:183], v195 offset:32768
	v_add_u32_e32 v194, 0xc000, v0
	s_waitcnt lgkmcnt(4)
	v_mfma_f32_32x32x16_bf16 v[128:143], v[238:241], v[190:193], v[128:143]
	ds_read_b128 v[238:241], v194
	s_waitcnt lgkmcnt(4)
	v_mfma_f32_32x32x16_bf16 v[48:63], v[242:245], v[190:193], v[48:63]
	ds_read_b128 v[242:245], v194 offset:4096
	s_waitcnt lgkmcnt(4)
	v_mfma_f32_32x32x16_bf16 v[32:47], v[246:249], v[190:193], v[32:47]
	ds_read_b128 v[246:249], v194 offset:8192
	s_waitcnt lgkmcnt(4)
	v_mfma_f32_32x32x16_bf16 v[16:31], v[250:253], v[190:193], v[16:31]
	ds_read_b128 v[250:253], v194 offset:12288
	v_add_u32_e32 v195, 0xc000, v234
	ds_read_b128 v[190:193], v195 offset:32768
	v_add_u32_e32 v194, 0xc000, v184
	s_waitcnt lgkmcnt(4)
	v_mfma_f32_32x32x16_bf16 v[128:143], v[238:241], v[180:183], v[128:143]
	ds_read_b128 v[238:241], v194
	s_waitcnt lgkmcnt(4)
	v_mfma_f32_32x32x16_bf16 v[48:63], v[242:245], v[180:183], v[48:63]
	ds_read_b128 v[242:245], v194 offset:4096
	s_waitcnt lgkmcnt(4)
	v_mfma_f32_32x32x16_bf16 v[32:47], v[246:249], v[180:183], v[32:47]
	ds_read_b128 v[246:249], v194 offset:8192
	s_waitcnt lgkmcnt(4)
	v_mfma_f32_32x32x16_bf16 v[16:31], v[250:253], v[180:183], v[16:31]
	ds_read_b128 v[250:253], v194 offset:12288
	s_waitcnt lgkmcnt(3)
	v_mfma_f32_32x32x16_bf16 v[128:143], v[238:241], v[190:193], v[128:143]
	s_waitcnt lgkmcnt(2)
	v_mfma_f32_32x32x16_bf16 v[48:63], v[242:245], v[190:193], v[48:63]
	s_waitcnt lgkmcnt(1)
	v_mfma_f32_32x32x16_bf16 v[32:47], v[246:249], v[190:193], v[32:47]
	s_waitcnt lgkmcnt(0)
	v_mfma_f32_32x32x16_bf16 v[16:31], v[250:253], v[190:193], v[16:31]
	s_waitcnt vmcnt(0)
	s_barrier
; DI unsigned pack2(float a, float b) { f2_t v = {a, b}; bf2_t r = __builtin_convertvector(v, bf2_t); return __builtin_bit_cast(unsigned, r); }
; DI f32x16 mfma(bf16x8 a, bf16x8 b, f32x16 c) { return __builtin_amdgcn_mfma_f32_32x32x16_bf16(a, b, c, 0, 0, 0); }
;     ...
;     for (int s = 0; s < 4; ++s) {
;       const int ro = ((2 * s + hh) ^ xr) * 16;
;       bf16x8 bfr[NTB];
; #pragma unroll
;       for (int tb = 0; tb < NTB; ++tb) bfr[tb] = *(const bf16x8*)(cur + bbase + tb * 32 * DROW + ro);
; #pragma unroll
;       for (int fb = 0; fb < NFB; ++fb) {
;         const bf16x8 afr = *(const bf16x8*)(cur + abase + fb * 32 * DROW + ro);
; #pragma unroll
;         for (int tb = 0; tb < NTB; ++tb) acc[tb * NFB + fb] = mfma(afr, bfr[tb], acc[tb * NFB + fb]);
;       }
;     }
;     asm volatile("s_waitcnt vmcnt(0) lgkmcnt(0)" ::: "memory");
;     __builtin_amdgcn_s_barrier();
; __global__ void __launch_bounds__(512) mega(Params p) {
;     ...
; #pragma unroll
;           for (int fb = 0; fb < 4; ++fb)
; #pragma unroll
;             for (int i = 0; i < 8; ++i) bp[fb][i] = pack2(acc[fb][2 * i], acc[fb][2 * i + 1]);
;           zero4(acc);
;           gemm_main<4, 1>((const u16*)(ws + OFF_WG) + ((size_t)n * 1024 + ft * 256) * 1024, 1024, (const u16*)(ws + OFF_H) + (size_t)tt * 128 * 1024, 1024, 16, acc, lds);
; #pragma unroll
;           for (int fb = 0; fb < 4; ++fb)
; #pragma unroll
;             for (int i = 0; i < 8; ++i) {
;               const float b0 = __uint_as_float(bp[fb][i] << 16), b1 = __uint_as_float(bp[fb][i] & 0xffff0000u);
;               const float g0 = 1.f / (1.f + __builtin_amdgcn_exp2f(nr1 * acc[fb][2 * i]));
;               const float g1 = 1.f / (1.f + __builtin_amdgcn_exp2f(nr1 * acc[fb][2 * i + 1]));
;               float y0 = g0 * b0, y1 = g1 * b1;
;               if (n > 0) { y0 += __uint_as_float(yp[fb][i] << 16); y1 += __uint_as_float(yp[fb][i] & 0xffff0000u); }
;               yp[fb][i] = pack2(y0, y1);
;             }
	v_add_u32_e32 v195, 0x18000, v186
	ds_read_b128 v[180:183], v195 offset:32768
	v_add_u32_e32 v194, 0x18000, v14
	ds_read_b128 v[238:241], v194
	ds_read_b128 v[242:245], v194 offset:4096
	ds_read_b128 v[246:249], v194 offset:8192
	ds_read_b128 v[250:253], v194 offset:12288
	v_add_u32_e32 v195, 0x18000, v189
	ds_read_b128 v[190:193], v195 offset:32768
	v_add_u32_e32 v194, 0x18000, v15
	s_waitcnt lgkmcnt(4)
	v_mfma_f32_32x32x16_bf16 v[128:143], v[238:241], v[180:183], v[128:143]
	ds_read_b128 v[238:241], v194
	s_waitcnt lgkmcnt(4)
	v_mfma_f32_32x32x16_bf16 v[48:63], v[242:245], v[180:183], v[48:63]
	ds_read_b128 v[242:245], v194 offset:4096
	s_waitcnt lgkmcnt(4)
	v_mfma_f32_32x32x16_bf16 v[32:47], v[246:249], v[180:183], v[32:47]
	ds_read_b128 v[246:249], v194 offset:8192
	s_waitcnt lgkmcnt(4)
	v_mfma_f32_32x32x16_bf16 v[16:31], v[250:253], v[180:183], v[16:31]
	ds_read_b128 v[250:253], v194 offset:12288
	v_add_u32_e32 v195, 0x18000, v233
	ds_read_b128 v[180:183], v195 offset:32768
	v_add_u32_e32 v194, 0x18000, v0
	s_waitcnt lgkmcnt(4)
	v_mfma_f32_32x32x16_bf16 v[128:143], v[238:241], v[190:193], v[128:143]
	ds_read_b128 v[238:241], v194
	s_waitcnt lgkmcnt(4)
	v_mfma_f32_32x32x16_bf16 v[48:63], v[242:245], v[190:193], v[48:63]
	ds_read_b128 v[242:245], v194 offset:4096
	s_waitcnt lgkmcnt(4)
	v_mfma_f32_32x32x16_bf16 v[32:47], v[246:249], v[190:193], v[32:47]
	ds_read_b128 v[246:249], v194 offset:8192
	s_waitcnt lgkmcnt(4)
	v_mfma_f32_32x32x16_bf16 v[16:31], v[250:253], v[190:193], v[16:31]
	ds_read_b128 v[250:253], v194 offset:12288
	v_add_u32_e32 v195, 0x18000, v234
	ds_read_b128 v[190:193], v195 offset:32768
	v_add_u32_e32 v194, 0x18000, v184
	s_waitcnt lgkmcnt(4)
	v_mfma_f32_32x32x16_bf16 v[128:143], v[238:241], v[180:183], v[128:143]
	ds_read_b128 v[238:241], v194
	s_waitcnt lgkmcnt(4)
	v_mfma_f32_32x32x16_bf16 v[48:63], v[242:245], v[180:183], v[48:63]
	ds_read_b128 v[242:245], v194 offset:4096
	s_waitcnt lgkmcnt(4)
	v_mfma_f32_32x32x16_bf16 v[32:47], v[246:249], v[180:183], v[32:47]
	ds_read_b128 v[246:249], v194 offset:8192
	s_waitcnt lgkmcnt(4)
	v_mfma_f32_32x32x16_bf16 v[16:31], v[250:253], v[180:183], v[16:31]
	ds_read_b128 v[250:253], v194 offset:12288
	s_waitcnt lgkmcnt(3)
	v_mfma_f32_32x32x16_bf16 v[128:143], v[238:241], v[190:193], v[128:143]
	s_waitcnt lgkmcnt(2)
	v_mfma_f32_32x32x16_bf16 v[48:63], v[242:245], v[190:193], v[48:63]
	s_waitcnt lgkmcnt(1)
	v_mfma_f32_32x32x16_bf16 v[32:47], v[246:249], v[190:193], v[32:47]
	s_waitcnt lgkmcnt(0)
	v_mfma_f32_32x32x16_bf16 v[16:31], v[250:253], v[190:193], v[16:31]
	s_nop 7
	s_nop 7
	s_waitcnt vmcnt(0) lgkmcnt(0)
	s_barrier
	v_cvt_pk_bf16_f32 v7, v66, v67
	v_mul_f32_e32 v66, v236, v128
	v_mul_f32_e32 v67, v236, v129
	v_exp_f32_e32 v66, v66
	v_exp_f32_e32 v67, v67
	v_cvt_pk_bf16_f32 v6, v68, v69
	v_cvt_pk_bf16_f32 v5, v70, v71
	v_cvt_pk_bf16_f32 v4, v72, v73
	v_pk_add_f32 v[66:67], v[66:67], 1.0 op_sel_hi:[1,0]
	v_cvt_pk_bf16_f32 v180, v112, v113
	v_cvt_pk_bf16_f32 v8, v64, v65
	v_lshlrev_b32_e32 v64, 16, v180
	v_and_b32_e32 v65, 0xffff0000, v180
	v_rcp_f32_e32 v67, v67
	v_cvt_pk_bf16_f32 v181, v114, v115
	v_cvt_pk_bf16_f32 v182, v116, v117
	v_cvt_pk_bf16_f32 v118, v118, v119
	v_rcp_f32_e32 v66, v66
	v_lshlrev_b32_e32 v70, 16, v166
	v_and_b32_e32 v71, 0xffff0000, v166
	v_pk_mul_f32 v[68:69], v[66:67], v[64:65]
	v_pk_fma_f32 v[64:65], v[66:67], v[64:65], v[70:71]
	v_mul_f32_e32 v66, v236, v130
	v_mul_f32_e32 v67, v236, v131
	v_exp_f32_e32 v66, v66
	v_exp_f32_e32 v67, v67
	v_cndmask_b32_e64 v64, v64, v68, s[0:1]
	v_cndmask_b32_e64 v65, v65, v69, s[0:1]
	v_cvt_pk_bf16_f32 v166, v64, v65
	v_pk_add_f32 v[66:67], v[66:67], 1.0 op_sel_hi:[1,0]
	v_lshlrev_b32_e32 v64, 16, v181
	v_and_b32_e32 v65, 0xffff0000, v181
	v_cvt_pk_bf16_f32 v117, v120, v121
	v_cvt_pk_bf16_f32 v116, v122, v123
	v_rcp_f32_e32 v67, v67
	v_cvt_pk_bf16_f32 v115, v124, v125
	v_mul_f32_e32 v48, v236, v48
	v_mul_f32_e32 v49, v236, v49
	v_rcp_f32_e32 v66, v66
	v_lshlrev_b32_e32 v70, 16, v167
	v_and_b32_e32 v71, 0xffff0000, v167
	v_pk_mul_f32 v[68:69], v[66:67], v[64:65]
	v_pk_fma_f32 v[64:65], v[66:67], v[64:65], v[70:71]
	v_mul_f32_e32 v66, v236, v132
	v_mul_f32_e32 v67, v236, v133
	v_exp_f32_e32 v66, v66
	v_exp_f32_e32 v67, v67
	v_cndmask_b32_e64 v64, v64, v68, s[0:1]
	v_cndmask_b32_e64 v65, v65, v69, s[0:1]
	v_cvt_pk_bf16_f32 v167, v64, v65
	v_pk_add_f32 v[66:67], v[66:67], 1.0 op_sel_hi:[1,0]
	v_lshlrev_b32_e32 v64, 16, v182
	v_and_b32_e32 v65, 0xffff0000, v182
	v_exp_f32_e32 v48, v48
	v_exp_f32_e32 v49, v49
	v_rcp_f32_e32 v67, v67
	v_cvt_pk_bf16_f32 v114, v126, v127
	v_pk_add_f32 v[48:49], v[48:49], 1.0 op_sel_hi:[1,0]
	v_mul_f32_e32 v50, v236, v50
	v_rcp_f32_e32 v66, v66
	v_lshlrev_b32_e32 v70, 16, v168
	v_and_b32_e32 v71, 0xffff0000, v168
	v_pk_mul_f32 v[68:69], v[66:67], v[64:65]
	v_pk_fma_f32 v[64:65], v[66:67], v[64:65], v[70:71]
	v_mul_f32_e32 v66, v236, v134
	v_mul_f32_e32 v67, v236, v135
	v_exp_f32_e32 v66, v66
	v_exp_f32_e32 v67, v67
	v_cndmask_b32_e64 v64, v64, v68, s[0:1]
	v_cndmask_b32_e64 v65, v65, v69, s[0:1]
	v_cvt_pk_bf16_f32 v168, v64, v65
	v_pk_add_f32 v[66:67], v[66:67], 1.0 op_sel_hi:[1,0]
	v_lshlrev_b32_e32 v64, 16, v118
	v_and_b32_e32 v65, 0xffff0000, v118
	v_mul_f32_e32 v51, v236, v51
	v_exp_f32_e32 v50, v50
	v_rcp_f32_e32 v67, v67
	v_exp_f32_e32 v51, v51
	v_cvt_pk_bf16_f32 v113, v96, v97
	v_cvt_pk_bf16_f32 v112, v98, v99
	v_rcp_f32_e32 v66, v66
	v_lshlrev_b32_e32 v70, 16, v169
	v_and_b32_e32 v71, 0xffff0000, v169
	v_pk_mul_f32 v[68:69], v[66:67], v[64:65]
	v_pk_fma_f32 v[64:65], v[66:67], v[64:65], v[70:71]
	v_mul_f32_e32 v66, v236, v136
	v_mul_f32_e32 v67, v236, v137
	v_exp_f32_e32 v66, v66
; DI unsigned pack2(float a, float b) { f2_t v = {a, b}; bf2_t r = __builtin_convertvector(v, bf2_t); return __builtin_bit_cast(unsigned, r); }
; __global__ void __launch_bounds__(512) mega(Params p) {
;     ...
; #pragma unroll
;           for (int fb = 0; fb < 4; ++fb)
; #pragma unroll
;             for (int i = 0; i < 8; ++i) {
;               const float b0 = __uint_as_float(bp[fb][i] << 16), b1 = __uint_as_float(bp[fb][i] & 0xffff0000u);
;               const float g0 = 1.f / (1.f + __builtin_amdgcn_exp2f(nr1 * acc[fb][2 * i]));
;               const float g1 = 1.f / (1.f + __builtin_amdgcn_exp2f(nr1 * acc[fb][2 * i + 1]));
;               float y0 = g0 * b0, y1 = g1 * b1;
;               if (n > 0) { y0 += __uint_as_float(yp[fb][i] << 16); y1 += __uint_as_float(yp[fb][i] & 0xffff0000u); }
;               yp[fb][i] = pack2(y0, y1);
;             }
	v_exp_f32_e32 v67, v67
	v_cndmask_b32_e64 v64, v64, v68, s[0:1]
	v_cndmask_b32_e64 v65, v65, v69, s[0:1]
	v_cvt_pk_bf16_f32 v169, v64, v65
	v_pk_add_f32 v[66:67], v[66:67], 1.0 op_sel_hi:[1,0]
	v_lshlrev_b32_e32 v64, 16, v117
	v_and_b32_e32 v65, 0xffff0000, v117
	v_pk_add_f32 v[50:51], v[50:51], 1.0 op_sel_hi:[1,0]
	v_cvt_pk_bf16_f32 v101, v100, v101
	v_rcp_f32_e32 v67, v67
	v_cvt_pk_bf16_f32 v100, v102, v103
	v_cvt_pk_bf16_f32 v99, v104, v105
	v_cvt_pk_bf16_f32 v98, v106, v107
	v_rcp_f32_e32 v66, v66
	v_lshlrev_b32_e32 v70, 16, v170
	v_and_b32_e32 v71, 0xffff0000, v170
	v_pk_mul_f32 v[68:69], v[66:67], v[64:65]
	v_pk_fma_f32 v[64:65], v[66:67], v[64:65], v[70:71]
	v_mul_f32_e32 v66, v236, v138
	v_mul_f32_e32 v67, v236, v139
	v_exp_f32_e32 v66, v66
	v_exp_f32_e32 v67, v67
	v_cndmask_b32_e64 v64, v64, v68, s[0:1]
	v_cndmask_b32_e64 v65, v65, v69, s[0:1]
	v_cvt_pk_bf16_f32 v170, v64, v65
	v_pk_add_f32 v[66:67], v[66:67], 1.0 op_sel_hi:[1,0]
	v_lshlrev_b32_e32 v64, 16, v116
	v_and_b32_e32 v65, 0xffff0000, v116
	v_cvt_pk_bf16_f32 v97, v108, v109
	v_mul_f32_e32 v32, v236, v32
	v_rcp_f32_e32 v67, v67
	v_mul_f32_e32 v33, v236, v33
	v_exp_f32_e32 v32, v32
	v_exp_f32_e32 v33, v33
	v_rcp_f32_e32 v66, v66
	v_lshlrev_b32_e32 v70, 16, v171
	v_and_b32_e32 v71, 0xffff0000, v171
	v_pk_mul_f32 v[68:69], v[66:67], v[64:65]
	v_pk_fma_f32 v[64:65], v[66:67], v[64:65], v[70:71]
	v_mul_f32_e32 v66, v236, v140
	v_mul_f32_e32 v67, v236, v141
	v_exp_f32_e32 v66, v66
	v_exp_f32_e32 v67, v67
	v_cndmask_b32_e64 v64, v64, v68, s[0:1]
	v_cndmask_b32_e64 v65, v65, v69, s[0:1]
	v_cvt_pk_bf16_f32 v171, v64, v65
	v_pk_add_f32 v[66:67], v[66:67], 1.0 op_sel_hi:[1,0]
	v_lshlrev_b32_e32 v64, 16, v115
	v_and_b32_e32 v65, 0xffff0000, v115
	v_cvt_pk_bf16_f32 v96, v110, v111
	v_pk_add_f32 v[32:33], v[32:33], 1.0 op_sel_hi:[1,0]
	v_rcp_f32_e32 v67, v67
	v_cvt_pk_bf16_f32 v80, v80, v81
	v_cvt_pk_bf16_f32 v15, v82, v83
	v_cvt_pk_bf16_f32 v14, v84, v85
	v_rcp_f32_e32 v66, v66
	v_lshlrev_b32_e32 v70, 16, v172
	v_and_b32_e32 v71, 0xffff0000, v172
	v_pk_mul_f32 v[68:69], v[66:67], v[64:65]
	v_pk_fma_f32 v[64:65], v[66:67], v[64:65], v[70:71]
	v_mul_f32_e32 v66, v236, v142
	v_mul_f32_e32 v67, v236, v143
	v_exp_f32_e32 v66, v66
	v_exp_f32_e32 v67, v67
	v_cndmask_b32_e64 v64, v64, v68, s[0:1]
	v_cndmask_b32_e64 v65, v65, v69, s[0:1]
	v_cvt_pk_bf16_f32 v172, v64, v65
	v_pk_add_f32 v[66:67], v[66:67], 1.0 op_sel_hi:[1,0]
	v_lshlrev_b32_e32 v64, 16, v114
	v_and_b32_e32 v65, 0xffff0000, v114
	v_cvt_pk_bf16_f32 v13, v86, v87
	v_cvt_pk_bf16_f32 v12, v88, v89
	v_rcp_f32_e32 v67, v67
	v_cvt_pk_bf16_f32 v11, v90, v91
	v_cvt_pk_bf16_f32 v10, v92, v93
	v_cvt_pk_bf16_f32 v9, v94, v95
	v_rcp_f32_e32 v66, v66
	v_lshlrev_b32_e32 v70, 16, v173
	v_and_b32_e32 v71, 0xffff0000, v173
	v_pk_mul_f32 v[68:69], v[66:67], v[64:65]
	v_pk_fma_f32 v[64:65], v[66:67], v[64:65], v[70:71]
	v_cndmask_b32_e64 v64, v64, v68, s[0:1]
	v_cndmask_b32_e64 v65, v65, v69, s[0:1]
	v_cvt_pk_bf16_f32 v173, v64, v65
	v_rcp_f32_e32 v49, v49
	v_lshlrev_b32_e32 v64, 16, v113
	v_and_b32_e32 v65, 0xffff0000, v113
	v_cvt_pk_bf16_f32 v3, v74, v75
	v_rcp_f32_e32 v48, v48
	v_lshlrev_b32_e32 v68, 16, v174
	v_and_b32_e32 v69, 0xffff0000, v174
	v_pk_mul_f32 v[66:67], v[48:49], v[64:65]
	v_pk_fma_f32 v[48:49], v[48:49], v[64:65], v[68:69]
	v_cndmask_b32_e64 v48, v48, v66, s[0:1]
	v_cndmask_b32_e64 v49, v49, v67, s[0:1]
	v_cvt_pk_bf16_f32 v174, v48, v49
	v_rcp_f32_e32 v51, v51
	v_lshlrev_b32_e32 v48, 16, v112
	v_and_b32_e32 v49, 0xffff0000, v112
	v_cvt_pk_bf16_f32 v2, v76, v77
	v_rcp_f32_e32 v50, v50
	v_lshlrev_b32_e32 v66, 16, v175
	v_and_b32_e32 v67, 0xffff0000, v175
	v_pk_mul_f32 v[64:65], v[50:51], v[48:49]
	v_pk_fma_f32 v[48:49], v[50:51], v[48:49], v[66:67]
	v_mul_f32_e32 v50, v236, v52
	v_mul_f32_e32 v51, v236, v53
	v_exp_f32_e32 v50, v50
	v_exp_f32_e32 v51, v51
	v_cndmask_b32_e64 v48, v48, v64, s[0:1]
	v_cndmask_b32_e64 v49, v49, v65, s[0:1]
	v_cvt_pk_bf16_f32 v175, v48, v49
	v_pk_add_f32 v[50:51], v[50:51], 1.0 op_sel_hi:[1,0]
	v_lshlrev_b32_e32 v48, 16, v101
	v_and_b32_e32 v49, 0xffff0000, v101
	v_cvt_pk_bf16_f32 v0, v78, v79
	s_add_i32 s8, s8, 1
	v_rcp_f32_e32 v51, v51
	s_cmp_eq_u32 s8, 3
	v_rcp_f32_e32 v50, v50
	v_lshlrev_b32_e32 v64, 16, v176
	v_and_b32_e32 v65, 0xffff0000, v176
	v_pk_mul_f32 v[52:53], v[50:51], v[48:49]
	v_pk_fma_f32 v[48:49], v[50:51], v[48:49], v[64:65]
	v_mul_f32_e32 v50, v236, v54
	v_mul_f32_e32 v51, v236, v55
	v_exp_f32_e32 v50, v50
	v_exp_f32_e32 v51, v51
	v_cndmask_b32_e64 v48, v48, v52, s[0:1]
	v_cndmask_b32_e64 v49, v49, v53, s[0:1]
	v_cvt_pk_bf16_f32 v176, v48, v49
	v_pk_add_f32 v[50:51], v[50:51], 1.0 op_sel_hi:[1,0]
	v_lshlrev_b32_e32 v48, 16, v100
	v_and_b32_e32 v49, 0xffff0000, v100
	v_rcp_f32_e32 v51, v51
	s_nop 0
	v_rcp_f32_e32 v50, v50
	v_lshlrev_b32_e32 v54, 16, v177
	v_and_b32_e32 v55, 0xffff0000, v177
	v_pk_mul_f32 v[52:53], v[50:51], v[48:49]
	v_pk_fma_f32 v[48:49], v[50:51], v[48:49], v[54:55]
	v_mul_f32_e32 v50, v236, v56
	v_mul_f32_e32 v51, v236, v57
	v_exp_f32_e32 v50, v50
	v_exp_f32_e32 v51, v51
	v_cndmask_b32_e64 v48, v48, v52, s[0:1]
	v_cndmask_b32_e64 v49, v49, v53, s[0:1]
	v_cvt_pk_bf16_f32 v177, v48, v49
	v_pk_add_f32 v[50:51], v[50:51], 1.0 op_sel_hi:[1,0]
	v_lshlrev_b32_e32 v48, 16, v99
	v_and_b32_e32 v49, 0xffff0000, v99
	v_rcp_f32_e32 v51, v51
	s_nop 0
	v_rcp_f32_e32 v50, v50
	v_lshlrev_b32_e32 v54, 16, v178
	v_and_b32_e32 v55, 0xffff0000, v178
	v_pk_mul_f32 v[52:53], v[50:51], v[48:49]
	v_pk_fma_f32 v[48:49], v[50:51], v[48:49], v[54:55]
	v_mul_f32_e32 v50, v236, v58
	v_mul_f32_e32 v51, v236, v59
	v_exp_f32_e32 v50, v50
	v_exp_f32_e32 v51, v51
	v_cndmask_b32_e64 v48, v48, v52, s[0:1]
; DI unsigned pack2(float a, float b) { f2_t v = {a, b}; bf2_t r = __builtin_convertvector(v, bf2_t); return __builtin_bit_cast(unsigned, r); }
; __global__ void __launch_bounds__(512) mega(Params p) {
;     ...
; #pragma unroll
;           for (int fb = 0; fb < 4; ++fb)
; #pragma unroll
;             for (int i = 0; i < 8; ++i) {
;               const float b0 = __uint_as_float(bp[fb][i] << 16), b1 = __uint_as_float(bp[fb][i] & 0xffff0000u);
;               const float g0 = 1.f / (1.f + __builtin_amdgcn_exp2f(nr1 * acc[fb][2 * i]));
;               const float g1 = 1.f / (1.f + __builtin_amdgcn_exp2f(nr1 * acc[fb][2 * i + 1]));
;               float y0 = g0 * b0, y1 = g1 * b1;
;               if (n > 0) { y0 += __uint_as_float(yp[fb][i] << 16); y1 += __uint_as_float(yp[fb][i] & 0xffff0000u); }
;               yp[fb][i] = pack2(y0, y1);
;             }
	v_cndmask_b32_e64 v49, v49, v53, s[0:1]
	v_cvt_pk_bf16_f32 v178, v48, v49
	v_pk_add_f32 v[50:51], v[50:51], 1.0 op_sel_hi:[1,0]
	v_lshlrev_b32_e32 v48, 16, v98
	v_and_b32_e32 v49, 0xffff0000, v98
	v_rcp_f32_e32 v51, v51
	s_nop 0
	v_rcp_f32_e32 v50, v50
	v_lshlrev_b32_e32 v54, 16, v179
	v_and_b32_e32 v55, 0xffff0000, v179
	v_pk_mul_f32 v[52:53], v[50:51], v[48:49]
	v_pk_fma_f32 v[48:49], v[50:51], v[48:49], v[54:55]
	v_mul_f32_e32 v50, v236, v60
	v_mul_f32_e32 v51, v236, v61
	v_exp_f32_e32 v50, v50
	v_exp_f32_e32 v51, v51
	v_cndmask_b32_e64 v48, v48, v52, s[0:1]
	v_cndmask_b32_e64 v49, v49, v53, s[0:1]
	v_cvt_pk_bf16_f32 v179, v48, v49
	v_pk_add_f32 v[50:51], v[50:51], 1.0 op_sel_hi:[1,0]
	v_lshlrev_b32_e32 v48, 16, v97
	v_and_b32_e32 v49, 0xffff0000, v97
	v_rcp_f32_e32 v51, v51
	s_nop 0
	v_rcp_f32_e32 v50, v50
	v_lshlrev_b32_e32 v54, 16, v164
	v_and_b32_e32 v55, 0xffff0000, v164
	v_pk_mul_f32 v[52:53], v[50:51], v[48:49]
	v_pk_fma_f32 v[48:49], v[50:51], v[48:49], v[54:55]
	v_mul_f32_e32 v50, v236, v62
	v_mul_f32_e32 v51, v236, v63
	v_exp_f32_e32 v50, v50
	v_exp_f32_e32 v51, v51
	v_cndmask_b32_e64 v48, v48, v52, s[0:1]
	v_cndmask_b32_e64 v49, v49, v53, s[0:1]
	v_cvt_pk_bf16_f32 v164, v48, v49
	v_pk_add_f32 v[50:51], v[50:51], 1.0 op_sel_hi:[1,0]
	v_lshlrev_b32_e32 v48, 16, v96
	v_and_b32_e32 v49, 0xffff0000, v96
	v_rcp_f32_e32 v51, v51
	s_nop 0
	v_rcp_f32_e32 v50, v50
	v_lshlrev_b32_e32 v54, 16, v165
	v_and_b32_e32 v55, 0xffff0000, v165
	v_pk_mul_f32 v[52:53], v[50:51], v[48:49]
	v_pk_fma_f32 v[48:49], v[50:51], v[48:49], v[54:55]
	v_cndmask_b32_e64 v48, v48, v52, s[0:1]
	v_cndmask_b32_e64 v49, v49, v53, s[0:1]
	v_cvt_pk_bf16_f32 v165, v48, v49
	v_rcp_f32_e32 v33, v33
	v_lshlrev_b32_e32 v48, 16, v80
	v_and_b32_e32 v49, 0xffff0000, v80
	v_rcp_f32_e32 v32, v32
	v_lshlrev_b32_e32 v52, 16, v162
	v_and_b32_e32 v53, 0xffff0000, v162
	v_pk_mul_f32 v[50:51], v[32:33], v[48:49]
	v_pk_fma_f32 v[32:33], v[32:33], v[48:49], v[52:53]
	s_nop 0
	v_cndmask_b32_e64 v33, v33, v51, s[0:1]
	v_cndmask_b32_e64 v32, v32, v50, s[0:1]
	v_cvt_pk_bf16_f32 v162, v32, v33
	v_lshlrev_b32_e32 v32, 16, v15
	v_and_b32_e32 v33, 0xffff0000, v15
	v_mul_f32_e32 v15, v236, v34
	v_exp_f32_e32 v34, v15
	v_mul_f32_e32 v15, v236, v35
	v_exp_f32_e32 v35, v15
	s_nop 0
	v_pk_add_f32 v[34:35], v[34:35], 1.0 op_sel_hi:[1,0]
	s_nop 0
	s_nop 0
	v_rcp_f32_e32 v35, v35
	s_nop 0
	v_rcp_f32_e32 v34, v34
	v_lshlrev_b32_e32 v50, 16, v163
	v_and_b32_e32 v51, 0xffff0000, v163
	v_pk_mul_f32 v[48:49], v[34:35], v[32:33]
	v_pk_fma_f32 v[32:33], v[34:35], v[32:33], v[50:51]
	s_nop 0
	v_cndmask_b32_e64 v15, v33, v49, s[0:1]
	v_cndmask_b32_e64 v32, v32, v48, s[0:1]
	v_cvt_pk_bf16_f32 v163, v32, v15
	v_lshlrev_b32_e32 v32, 16, v14
	v_and_b32_e32 v33, 0xffff0000, v14
	v_mul_f32_e32 v14, v236, v36
	v_mul_f32_e32 v15, v236, v37
	v_exp_f32_e32 v14, v14
	v_exp_f32_e32 v15, v15
	s_nop 0
	v_pk_add_f32 v[14:15], v[14:15], 1.0 op_sel_hi:[1,0]
	s_nop 0
	s_nop 0
	v_rcp_f32_e32 v15, v15
	s_nop 0
	v_rcp_f32_e32 v14, v14
	v_lshlrev_b32_e32 v36, 16, v160
	v_and_b32_e32 v37, 0xffff0000, v160
	v_pk_mul_f32 v[34:35], v[14:15], v[32:33]
	v_pk_fma_f32 v[14:15], v[14:15], v[32:33], v[36:37]
	s_nop 0
	v_cndmask_b32_e64 v15, v15, v35, s[0:1]
	v_cndmask_b32_e64 v14, v14, v34, s[0:1]
	v_cvt_pk_bf16_f32 v160, v14, v15
	v_lshlrev_b32_e32 v14, 16, v13
	v_and_b32_e32 v15, 0xffff0000, v13
	v_mul_f32_e32 v13, v236, v38
	v_exp_f32_e32 v32, v13
	v_mul_f32_e32 v13, v236, v39
	v_exp_f32_e32 v33, v13
	s_nop 0
	v_pk_add_f32 v[32:33], v[32:33], 1.0 op_sel_hi:[1,0]
	s_nop 0
	s_nop 0
	v_rcp_f32_e32 v33, v33
	s_nop 0
	v_rcp_f32_e32 v32, v32
	v_lshlrev_b32_e32 v36, 16, v161
	v_and_b32_e32 v37, 0xffff0000, v161
	v_pk_mul_f32 v[34:35], v[32:33], v[14:15]
	v_pk_fma_f32 v[14:15], v[32:33], v[14:15], v[36:37]
	s_nop 0
	v_cndmask_b32_e64 v13, v15, v35, s[0:1]
	v_cndmask_b32_e64 v14, v14, v34, s[0:1]
	v_cvt_pk_bf16_f32 v161, v14, v13
	v_lshlrev_b32_e32 v14, 16, v12
	v_and_b32_e32 v15, 0xffff0000, v12
	v_mul_f32_e32 v12, v236, v40
	v_mul_f32_e32 v13, v236, v41
	v_exp_f32_e32 v12, v12
	v_exp_f32_e32 v13, v13
	s_nop 0
	v_pk_add_f32 v[12:13], v[12:13], 1.0 op_sel_hi:[1,0]
	s_nop 0
	s_nop 0
	v_rcp_f32_e32 v13, v13
	s_nop 0
	v_rcp_f32_e32 v12, v12
	v_lshlrev_b32_e32 v34, 16, v158
	v_and_b32_e32 v35, 0xffff0000, v158
	v_pk_mul_f32 v[32:33], v[12:13], v[14:15]
	v_pk_fma_f32 v[12:13], v[12:13], v[14:15], v[34:35]
	s_nop 0
	v_cndmask_b32_e64 v13, v13, v33, s[0:1]
	v_cndmask_b32_e64 v12, v12, v32, s[0:1]
	v_cvt_pk_bf16_f32 v158, v12, v13
	v_lshlrev_b32_e32 v12, 16, v11
	v_and_b32_e32 v13, 0xffff0000, v11
	v_mul_f32_e32 v11, v236, v42
	v_exp_f32_e32 v14, v11
	v_mul_f32_e32 v11, v236, v43
	v_exp_f32_e32 v15, v11
	s_nop 0
	v_pk_add_f32 v[14:15], v[14:15], 1.0 op_sel_hi:[1,0]
	s_nop 0
	s_nop 0
	v_rcp_f32_e32 v15, v15
	s_nop 0
	v_rcp_f32_e32 v14, v14
	v_lshlrev_b32_e32 v34, 16, v159
	v_and_b32_e32 v35, 0xffff0000, v159
	v_pk_mul_f32 v[32:33], v[14:15], v[12:13]
	v_pk_fma_f32 v[12:13], v[14:15], v[12:13], v[34:35]
	s_nop 0
	v_cndmask_b32_e64 v11, v13, v33, s[0:1]
	v_cndmask_b32_e64 v12, v12, v32, s[0:1]
	v_cvt_pk_bf16_f32 v159, v12, v11
	v_lshlrev_b32_e32 v12, 16, v10
	v_and_b32_e32 v13, 0xffff0000, v10
	v_mul_f32_e32 v10, v236, v44
	v_mul_f32_e32 v11, v236, v45
	v_exp_f32_e32 v10, v10
	v_exp_f32_e32 v11, v11
	s_nop 0
	v_pk_add_f32 v[10:11], v[10:11], 1.0 op_sel_hi:[1,0]
	s_nop 0
	s_nop 0
	v_rcp_f32_e32 v11, v11
	s_nop 0
	v_rcp_f32_e32 v10, v10
	v_lshlrev_b32_e32 v32, 16, v156
	v_and_b32_e32 v33, 0xffff0000, v156
	v_pk_mul_f32 v[14:15], v[10:11], v[12:13]
	v_pk_fma_f32 v[10:11], v[10:11], v[12:13], v[32:33]
	s_nop 0
	v_cndmask_b32_e64 v11, v11, v15, s[0:1]
; DI unsigned pack2(float a, float b) { f2_t v = {a, b}; bf2_t r = __builtin_convertvector(v, bf2_t); return __builtin_bit_cast(unsigned, r); }
; __global__ void __launch_bounds__(512) mega(Params p) {
;     ...
; #pragma unroll
;           for (int fb = 0; fb < 4; ++fb)
; #pragma unroll
;             for (int i = 0; i < 8; ++i) {
;               const float b0 = __uint_as_float(bp[fb][i] << 16), b1 = __uint_as_float(bp[fb][i] & 0xffff0000u);
;               const float g0 = 1.f / (1.f + __builtin_amdgcn_exp2f(nr1 * acc[fb][2 * i]));
;               const float g1 = 1.f / (1.f + __builtin_amdgcn_exp2f(nr1 * acc[fb][2 * i + 1]));
;               float y0 = g0 * b0, y1 = g1 * b1;
;               if (n > 0) { y0 += __uint_as_float(yp[fb][i] << 16); y1 += __uint_as_float(yp[fb][i] & 0xffff0000u); }
;               yp[fb][i] = pack2(y0, y1);
;             }
;         }
;         __syncthreads();
; #pragma unroll
;         for (int fb = 0; fb < 4; ++fb)
; #pragma unroll
;           for (int jq = 0; jq < 4; ++jq)
;             *(uint2*)(lds + (wt * 32 + l32) * EROW + (wf * 128 + fb * 32 + 8 * jq + 4 * hh) * 2) = make_uint2(yp[fb][2 * jq], yp[fb][2 * jq + 1]);
;         epi_flush<128>(lds, (u16*)(ws + R_Y) + (size_t)tt * 128 * 1024 + ft * 256, 1024);
	v_cndmask_b32_e64 v10, v10, v14, s[0:1]
	v_cvt_pk_bf16_f32 v156, v10, v11
	v_lshlrev_b32_e32 v10, 16, v9
	v_and_b32_e32 v11, 0xffff0000, v9
	v_mul_f32_e32 v9, v236, v46
	v_exp_f32_e32 v12, v9
	v_mul_f32_e32 v9, v236, v47
	v_exp_f32_e32 v13, v9
	s_nop 0
	v_pk_add_f32 v[12:13], v[12:13], 1.0 op_sel_hi:[1,0]
	s_nop 0
	s_nop 0
	v_rcp_f32_e32 v13, v13
	s_nop 0
	v_rcp_f32_e32 v12, v12
	v_lshlrev_b32_e32 v32, 16, v157
	v_and_b32_e32 v33, 0xffff0000, v157
	v_pk_mul_f32 v[14:15], v[12:13], v[10:11]
	v_pk_fma_f32 v[10:11], v[12:13], v[10:11], v[32:33]
	s_nop 0
	v_cndmask_b32_e64 v9, v11, v15, s[0:1]
	v_cndmask_b32_e64 v10, v10, v14, s[0:1]
	v_cvt_pk_bf16_f32 v157, v10, v9
	v_lshlrev_b32_e32 v10, 16, v8
	v_and_b32_e32 v11, 0xffff0000, v8
	v_mul_f32_e32 v8, v236, v16
	v_mul_f32_e32 v9, v236, v17
	v_exp_f32_e32 v8, v8
	v_exp_f32_e32 v9, v9
	s_nop 0
	v_pk_add_f32 v[8:9], v[8:9], 1.0 op_sel_hi:[1,0]
	s_nop 0
	s_nop 0
	v_rcp_f32_e32 v9, v9
	s_nop 0
	v_rcp_f32_e32 v8, v8
	v_lshlrev_b32_e32 v14, 16, v154
	v_and_b32_e32 v15, 0xffff0000, v154
	v_pk_mul_f32 v[12:13], v[8:9], v[10:11]
	v_pk_fma_f32 v[8:9], v[8:9], v[10:11], v[14:15]
	s_nop 0
	v_cndmask_b32_e64 v9, v9, v13, s[0:1]
	v_cndmask_b32_e64 v8, v8, v12, s[0:1]
	v_cvt_pk_bf16_f32 v154, v8, v9
	v_lshlrev_b32_e32 v8, 16, v7
	v_and_b32_e32 v9, 0xffff0000, v7
	v_mul_f32_e32 v7, v236, v18
	v_exp_f32_e32 v10, v7
	v_mul_f32_e32 v7, v236, v19
	v_exp_f32_e32 v11, v7
	s_nop 0
	v_pk_add_f32 v[10:11], v[10:11], 1.0 op_sel_hi:[1,0]
	s_nop 0
	s_nop 0
	v_rcp_f32_e32 v11, v11
	s_nop 0
	v_rcp_f32_e32 v10, v10
	v_lshlrev_b32_e32 v14, 16, v155
	v_and_b32_e32 v15, 0xffff0000, v155
	v_pk_mul_f32 v[12:13], v[10:11], v[8:9]
	v_pk_fma_f32 v[8:9], v[10:11], v[8:9], v[14:15]
	s_nop 0
	v_cndmask_b32_e64 v7, v9, v13, s[0:1]
	v_cndmask_b32_e64 v8, v8, v12, s[0:1]
	v_cvt_pk_bf16_f32 v155, v8, v7
	v_lshlrev_b32_e32 v8, 16, v6
	v_and_b32_e32 v9, 0xffff0000, v6
	v_mul_f32_e32 v6, v236, v20
	v_mul_f32_e32 v7, v236, v21
	v_exp_f32_e32 v6, v6
	v_exp_f32_e32 v7, v7
	s_nop 0
	v_pk_add_f32 v[6:7], v[6:7], 1.0 op_sel_hi:[1,0]
	s_nop 0
	s_nop 0
	v_rcp_f32_e32 v7, v7
	s_nop 0
	v_rcp_f32_e32 v6, v6
	v_lshlrev_b32_e32 v12, 16, v152
	v_and_b32_e32 v13, 0xffff0000, v152
	v_pk_mul_f32 v[10:11], v[6:7], v[8:9]
	v_pk_fma_f32 v[6:7], v[6:7], v[8:9], v[12:13]
	s_nop 0
	v_cndmask_b32_e64 v7, v7, v11, s[0:1]
	v_cndmask_b32_e64 v6, v6, v10, s[0:1]
	v_cvt_pk_bf16_f32 v152, v6, v7
	v_lshlrev_b32_e32 v6, 16, v5
	v_and_b32_e32 v7, 0xffff0000, v5
	v_mul_f32_e32 v5, v236, v22
	v_exp_f32_e32 v8, v5
	v_mul_f32_e32 v5, v236, v23
	v_exp_f32_e32 v9, v5
	s_nop 0
	v_pk_add_f32 v[8:9], v[8:9], 1.0 op_sel_hi:[1,0]
	s_nop 0
	s_nop 0
	v_rcp_f32_e32 v9, v9
	s_nop 0
	v_rcp_f32_e32 v8, v8
	v_lshlrev_b32_e32 v12, 16, v153
	v_and_b32_e32 v13, 0xffff0000, v153
	v_pk_mul_f32 v[10:11], v[8:9], v[6:7]
	v_pk_fma_f32 v[6:7], v[8:9], v[6:7], v[12:13]
	s_nop 0
	v_cndmask_b32_e64 v5, v7, v11, s[0:1]
	v_cndmask_b32_e64 v6, v6, v10, s[0:1]
	v_cvt_pk_bf16_f32 v153, v6, v5
	v_lshlrev_b32_e32 v6, 16, v4
	v_and_b32_e32 v7, 0xffff0000, v4
	v_mul_f32_e32 v4, v236, v24
	v_mul_f32_e32 v5, v236, v25
	v_exp_f32_e32 v4, v4
	v_exp_f32_e32 v5, v5
	s_nop 0
	v_pk_add_f32 v[4:5], v[4:5], 1.0 op_sel_hi:[1,0]
	s_nop 0
	s_nop 0
	v_rcp_f32_e32 v5, v5
	s_nop 0
	v_rcp_f32_e32 v4, v4
	v_lshlrev_b32_e32 v10, 16, v150
	v_and_b32_e32 v11, 0xffff0000, v150
	v_pk_mul_f32 v[8:9], v[4:5], v[6:7]
	v_pk_fma_f32 v[4:5], v[4:5], v[6:7], v[10:11]
	s_nop 0
	v_cndmask_b32_e64 v5, v5, v9, s[0:1]
	v_cndmask_b32_e64 v4, v4, v8, s[0:1]
	v_cvt_pk_bf16_f32 v150, v4, v5
	v_lshlrev_b32_e32 v4, 16, v3
	v_and_b32_e32 v5, 0xffff0000, v3
	v_mul_f32_e32 v3, v236, v26
	v_exp_f32_e32 v6, v3
	v_mul_f32_e32 v3, v236, v27
	v_exp_f32_e32 v7, v3
	s_nop 0
	v_pk_add_f32 v[6:7], v[6:7], 1.0 op_sel_hi:[1,0]
	s_nop 0
	s_nop 0
	v_rcp_f32_e32 v7, v7
	s_nop 0
	v_rcp_f32_e32 v6, v6
	v_lshlrev_b32_e32 v10, 16, v151
	v_and_b32_e32 v11, 0xffff0000, v151
	v_pk_mul_f32 v[8:9], v[6:7], v[4:5]
	v_pk_fma_f32 v[4:5], v[6:7], v[4:5], v[10:11]
	s_nop 0
	v_cndmask_b32_e64 v3, v5, v9, s[0:1]
	v_cndmask_b32_e64 v4, v4, v8, s[0:1]
	v_cvt_pk_bf16_f32 v151, v4, v3
	v_lshlrev_b32_e32 v4, 16, v2
	v_and_b32_e32 v5, 0xffff0000, v2
	v_mul_f32_e32 v2, v236, v28
	v_mul_f32_e32 v3, v236, v29
	v_exp_f32_e32 v2, v2
	v_exp_f32_e32 v3, v3
	s_nop 0
	v_pk_add_f32 v[2:3], v[2:3], 1.0 op_sel_hi:[1,0]
	s_nop 0
	s_nop 0
	v_rcp_f32_e32 v3, v3
	s_nop 0
	v_rcp_f32_e32 v2, v2
	v_lshlrev_b32_e32 v8, 16, v148
	v_and_b32_e32 v9, 0xffff0000, v148
	v_pk_mul_f32 v[6:7], v[2:3], v[4:5]
	v_pk_fma_f32 v[2:3], v[2:3], v[4:5], v[8:9]
	s_nop 0
	v_cndmask_b32_e64 v3, v3, v7, s[0:1]
	v_cndmask_b32_e64 v2, v2, v6, s[0:1]
	v_cvt_pk_bf16_f32 v148, v2, v3
	v_lshlrev_b32_e32 v2, 16, v0
	v_and_b32_e32 v3, 0xffff0000, v0
	v_mul_f32_e32 v0, v236, v30
	v_exp_f32_e32 v4, v0
	v_mul_f32_e32 v0, v236, v31
	v_exp_f32_e32 v5, v0
	s_nop 0
	v_pk_add_f32 v[4:5], v[4:5], 1.0 op_sel_hi:[1,0]
	s_nop 0
	s_nop 0
	v_rcp_f32_e32 v5, v5
	s_nop 0
	v_rcp_f32_e32 v4, v4
	v_lshlrev_b32_e32 v8, 16, v149
	v_and_b32_e32 v9, 0xffff0000, v149
	v_pk_mul_f32 v[6:7], v[4:5], v[2:3]
	v_pk_fma_f32 v[2:3], v[4:5], v[2:3], v[8:9]
	s_nop 0
	v_cndmask_b32_e64 v0, v3, v7, s[0:1]
	v_cndmask_b32_e64 v2, v2, v6, s[0:1]
	v_cvt_pk_bf16_f32 v149, v2, v0
	s_cbranch_scc0 .LBB0_25
	v_mov_b32_e32 v6, v145
	s_waitcnt vmcnt(0)
	s_barrier
	ds_write2_b64 v235, v[166:167], v[168:169] offset1:2
	ds_write2_b64 v235, v[170:171], v[172:173] offset0:4 offset1:6
	ds_write2_b64 v235, v[174:175], v[176:177] offset0:8 offset1:10
	ds_write2_b64 v235, v[178:179], v[164:165] offset0:12 offset1:14
	ds_write2_b64 v235, v[162:163], v[160:161] offset0:16 offset1:18
	ds_write2_b64 v235, v[158:159], v[156:157] offset0:20 offset1:22
	ds_write2_b64 v235, v[154:155], v[152:153] offset0:24 offset1:26
	ds_write2_b64 v235, v[150:151], v[148:149] offset0:28 offset1:30
	s_waitcnt lgkmcnt(0)
	v_ashrrev_i32_e32 v2, 5, v6
	v_cmp_gt_i32_e32 vcc, s70, v2
	s_barrier
	s_and_saveexec_b64 s[0:1], vcc
	s_cbranch_execz .LBB0_23
	v_max_i32_e32 v0, 0x70, v2
	v_sub_u32_e32 v0, v0, v2
	v_add_u32_e32 v0, 15, v0
	v_and_b32_e32 v4, 31, v6
	v_and_b32_e32 v3, 48, v0
	s_and_b32 s33, s52, 0xe0
	v_lshlrev_b32_e32 v12, 4, v4
	v_cmp_ne_u32_e32 vcc, 48, v3
	s_and_saveexec_b64 s[8:9], vcc
	s_cbranch_execz .LBB0_55
	v_lshrrev_b32_e32 v3, 4, v0
	s_add_i32 s34, s33, s57
	v_add_u32_e32 v3, 1, v3
	s_add_i32 s34, s34, s58
	v_and_b32_e32 v7, 3, v3
	s_ashr_i32 s35, s34, 31
	v_ashrrev_i32_e32 v3, 31, v2
	s_lshl_b64 s[34:35], s[34:35], 18
	v_lshlrev_b64 v[8:9], 11, v[2:3]
	v_lshl_add_u64 v[8:9], s[34:35], 0, v[8:9]
	s_lshl_b64 s[34:35], s[54:55], 1
	s_add_u32 s34, s10, s34
	v_lshl_or_b32 v8, v4, 4, v8
	s_addc_u32 s35, s11, s35
	v_lshl_add_u64 v[4:5], s[34:35], 0, v[8:9]
	s_movk_i32 s34, 0x210
	v_mul_lo_u32 v3, v2, s34
	v_add3_u32 v3, v3, v12, 0
	v_sub_u32_e32 v7, 0, v7
	s_mov_b64 s[34:35], 0
	s_mov_b64 s[64:65], 0x8000
